# GUP fast-path epilogue: paired 16B bf16 stores, DPP movs folded into FMAs
# speedup vs baseline: 1.0056x; 1.0009x over previous
;     __device__ __forceinline__ void operator()(const f32x4 (&acc)[2][2][4][2], const pg8::Unit& u, int wr, int wc, int fr, int fq) const {
;     ...
;             for (int n = 0; n < 2; ++n) {
;                 f32x4 wv[3], wg[3], bv, bg;
; #pragma unroll
;                 for (int k = 0; k < 3; ++k) { wv[k] = *(const f32x4*)(cw + k * 6144 + cv + 4 * n); wg[k] = *(const f32x4*)(cw + k * 6144 + DFF + cv + 4 * n); }
;                 bv = *(const f32x4*)(cbias + cv + 4 * n); bg = *(const f32x4*)(cbias + DFF + cv + 4 * n);
; #pragma unroll
;                 for (int ai = 0; ai < 2; ++ai) { const int s = 2 * ai + wr;
; #pragma unroll
;                     for (int m = 0; m < 4; ++m) {
;                         const int rl = 128 * ai + 64 * wr + 16 * m + fr, row = R0 + rl;
;                         f32x4 xpv, xpg, xnv, xng;
;                         if (m == 0) { const LAS float* p = xb + ((s > 0 ? s - 1 : 0) * 2 + 1) * 256 + cl + 4 * n; xpv = *(const LAS f32x4*)p; xpg = *(const LAS f32x4*)(p + 128); }
;                         if (m == 3) { const LAS float* p = xb + ((s < 3 ? s + 1 : 3) * 2 + 0) * 256 + cl + 4 * n; xnv = *(const LAS f32x4*)p; xng = *(const LAS f32x4*)(p + 128); }
;                         float o[4];
; #pragma unroll
;                         for (int e = 0; e < 4; ++e) {
;                             const float cvv = acc[ai][0][m][n][e], cgg = acc[ai][1][m][n][e];
;                             const float upv = m > 0 ? acc[ai][0][m > 0 ? m - 1 : 0][n][e] : xpv[e], upg = m > 0 ? acc[ai][1][m > 0 ? m - 1 : 0][n][e] : xpg[e];
;                             const float dnv = m < 3 ? acc[ai][0][m < 3 ? m + 1 : 3][n][e] : xnv[e], dng = m < 3 ? acc[ai][1][m < 3 ? m + 1 : 3][n][e] : xng[e];
;                             const float xpv_ = fr == 15 ? upv : cvv, xpg_ = fr == 15 ? upg : cgg;
;                             const float xnv_ = fr == 0 ? dnv : cvv, xng_ = fr == 0 ? dng : cgg;
;                             float val = bv[e] + wv[1][e] * cvv; val += wv[0][e] * dppf<0x121>(xpv_); val += wv[2][e] * dppf<0x12F>(xnv_);
;                             float gt = bg[e] + wg[1][e] * cgg; gt += wg[0][e] * dppf<0x121>(xpg_); gt += wg[2][e] * dppf<0x12F>(xng_);
;                             o[e] = val * gt * sigmoidf_(gt);
;                         }
;                         u32x2 ow; ow.x = pg8::cvt_pk_bf16(o[0], o[1]); ow.y = pg8::cvt_pk_bf16(o[2], o[3]);
.LBB0_434:
	global_load_dwordx4 v[142:145], v[196:197], off
	global_load_dwordx4 v[138:141], v[194:195], off
	global_load_dwordx4 v[158:161], v[198:199], off
	global_load_dwordx4 v[134:137], v[202:203], off
	global_load_dwordx4 v[154:157], v[204:205], off
	global_load_dwordx4 v[146:149], v[192:193], off
	global_load_dwordx4 v[150:153], v[200:201], off
	ds_read_b128 v[162:165], v234
	ds_read_b128 v[166:169], v234 offset:512
	v_cndmask_b32_e64 v170, v122, v114, s[40:41]
	s_waitcnt lgkmcnt(0)
	v_cndmask_b32_e64 v48, v126, v162, s[42:43]
	v_cndmask_b32_e64 v162, v122, v166, s[42:43]
	v_cndmask_b32_e64 v166, v126, v118, s[40:41]
	s_waitcnt vmcnt(0)
	v_fma_f32 v171, v126, v138, v146
	v_fmac_f32_dpp v171, v48, v130 row_ror:1 row_mask:0xf bank_mask:0xf bound_ctrl:1
	v_fmac_f32_dpp v171, v166, v134 row_ror:15 row_mask:0xf bank_mask:0xf bound_ctrl:1
	v_fma_f32 v48, v122, v158, v150
	v_fmac_f32_dpp v48, v162, v142 row_ror:1 row_mask:0xf bank_mask:0xf bound_ctrl:1
	v_fmac_f32_dpp v48, v170, v154 row_ror:15 row_mask:0xf bank_mask:0xf bound_ctrl:1
	v_mul_f32_e32 v162, v171, v48
	v_mul_f32_e32 v48, 0xbfb8aa3b, v48
	v_exp_f32_e32 v48, v48
	v_cndmask_b32_e64 v166, v127, v119, s[40:41]
	v_fma_f32 v170, v127, v139, v147
	v_add_f32_e32 v48, 1.0, v48
	v_rcp_f32_e32 v48, v48
	s_nop 0
	v_mul_f32_e32 v48, v162, v48
	v_cndmask_b32_e64 v162, v127, v163, s[42:43]
	v_cndmask_b32_e64 v163, v123, v167, s[42:43]
	v_cndmask_b32_e64 v167, v123, v115, s[40:41]
	v_fmac_f32_dpp v170, v162, v131 row_ror:1 row_mask:0xf bank_mask:0xf bound_ctrl:1
	v_fmac_f32_dpp v170, v166, v135 row_ror:15 row_mask:0xf bank_mask:0xf bound_ctrl:1
	v_fma_f32 v162, v123, v159, v151
	v_fmac_f32_dpp v162, v163, v143 row_ror:1 row_mask:0xf bank_mask:0xf bound_ctrl:1
	v_fmac_f32_dpp v162, v167, v155 row_ror:15 row_mask:0xf bank_mask:0xf bound_ctrl:1
	v_mul_f32_e32 v163, v170, v162
	v_mul_f32_e32 v162, 0xbfb8aa3b, v162
	v_exp_f32_e32 v162, v162
	v_cndmask_b32_e64 v166, v128, v120, s[40:41]
	v_cndmask_b32_e64 v167, v124, v116, s[40:41]
	v_add_f32_e32 v162, 1.0, v162
	v_rcp_f32_e32 v162, v162
	s_nop 0
	v_mul_f32_e32 v162, v163, v162
	v_cndmask_b32_e64 v163, v128, v164, s[42:43]
	v_cndmask_b32_e64 v164, v124, v168, s[42:43]
	v_fma_f32 v168, v128, v140, v148
	v_fmac_f32_dpp v168, v163, v132 row_ror:1 row_mask:0xf bank_mask:0xf bound_ctrl:1
	v_fmac_f32_dpp v168, v166, v136 row_ror:15 row_mask:0xf bank_mask:0xf bound_ctrl:1
	v_fma_f32 v163, v124, v160, v152
	v_fmac_f32_dpp v163, v164, v144 row_ror:1 row_mask:0xf bank_mask:0xf bound_ctrl:1
	v_fmac_f32_dpp v163, v167, v156 row_ror:15 row_mask:0xf bank_mask:0xf bound_ctrl:1
	v_mul_f32_e32 v164, v168, v163
	v_mul_f32_e32 v163, 0xbfb8aa3b, v163
	v_exp_f32_e32 v163, v163
	v_cndmask_b32_e64 v166, v129, v121, s[40:41]
	v_fma_f32 v168, v129, v141, v149
	v_cndmask_b32_e64 v167, v125, v117, s[40:41]
	v_add_f32_e32 v163, 1.0, v163
	v_rcp_f32_e32 v163, v163
	v_cvt_pk_bf16_f32 v162, v48, v162
	s_nop 0
	v_mul_f32_e32 v163, v164, v163
	v_cndmask_b32_e64 v164, v129, v165, s[42:43]
	v_cndmask_b32_e64 v165, v125, v169, s[42:43]
	s_nop 0
	v_fmac_f32_dpp v168, v164, v133 row_ror:1 row_mask:0xf bank_mask:0xf bound_ctrl:1
	v_fmac_f32_dpp v168, v166, v137 row_ror:15 row_mask:0xf bank_mask:0xf bound_ctrl:1
	v_fma_f32 v164, v125, v161, v153
	v_fmac_f32_dpp v164, v165, v145 row_ror:1 row_mask:0xf bank_mask:0xf bound_ctrl:1
	v_fmac_f32_dpp v164, v167, v157 row_ror:15 row_mask:0xf bank_mask:0xf bound_ctrl:1
	v_mul_f32_e32 v165, v168, v164
	v_mul_f32_e32 v164, 0xbfb8aa3b, v164
	v_exp_f32_e32 v164, v164
	s_nop 0
	v_add_f32_e32 v164, 1.0, v164
	v_rcp_f32_e32 v164, v164
	s_nop 0
	v_mul_f32_e32 v164, v165, v164
	v_cvt_pk_bf16_f32 v163, v163, v164
	s_nop 0
	v_mov_b32_e32 v172, v162
	v_mov_b32_e32 v173, v163
	v_cndmask_b32_e64 v122, v114, v122, s[42:43]
	v_cndmask_b32_e64 v163, v114, v106, s[40:41]
	v_fma_f32 v164, v114, v158, v150
	v_cndmask_b32_e64 v126, v118, v126, s[42:43]
	v_fmac_f32_dpp v164, v122, v142 row_ror:1 row_mask:0xf bank_mask:0xf bound_ctrl:1
	v_cndmask_b32_e64 v162, v118, v110, s[40:41]
	v_fmac_f32_dpp v164, v163, v154 row_ror:15 row_mask:0xf bank_mask:0xf bound_ctrl:1
	v_fma_f32 v163, v118, v138, v146
	v_mul_f32_e32 v122, 0xbfb8aa3b, v164
	v_fmac_f32_dpp v163, v126, v130 row_ror:1 row_mask:0xf bank_mask:0xf bound_ctrl:1
	v_exp_f32_e32 v122, v122
	v_fmac_f32_dpp v163, v162, v134 row_ror:15 row_mask:0xf bank_mask:0xf bound_ctrl:1
	v_cndmask_b32_e64 v123, v115, v123, s[42:43]
	v_mul_f32_e32 v126, v163, v164
	v_cndmask_b32_e64 v162, v115, v107, s[40:41]
	v_fma_f32 v163, v115, v159, v151
	v_fmac_f32_dpp v163, v123, v143 row_ror:1 row_mask:0xf bank_mask:0xf bound_ctrl:1
	v_add_f32_e32 v122, 1.0, v122
	v_fmac_f32_dpp v163, v162, v155 row_ror:15 row_mask:0xf bank_mask:0xf bound_ctrl:1
	v_mul_f32_e32 v123, 0xbfb8aa3b, v163
	v_rcp_f32_e32 v122, v122
	v_exp_f32_e32 v123, v123
	v_fma_f32 v162, v119, v139, v147
	v_cndmask_b32_e64 v124, v116, v124, s[42:43]
	v_mul_f32_e32 v122, v126, v122
	v_cndmask_b32_e64 v126, v119, v127, s[42:43]
	v_add_f32_e32 v123, 1.0, v123
	v_cndmask_b32_e64 v127, v119, v111, s[40:41]
	v_rcp_f32_e32 v123, v123
	v_fmac_f32_dpp v162, v126, v131 row_ror:1 row_mask:0xf bank_mask:0xf bound_ctrl:1
	v_fmac_f32_dpp v162, v127, v135 row_ror:15 row_mask:0xf bank_mask:0xf bound_ctrl:1
	v_mul_f32_e32 v126, v162, v163
	v_mul_f32_e32 v123, v126, v123
	v_cndmask_b32_e64 v126, v120, v128, s[42:43]
	v_cndmask_b32_e64 v128, v116, v108, s[40:41]
	v_fma_f32 v162, v116, v160, v152
	v_fmac_f32_dpp v162, v124, v144 row_ror:1 row_mask:0xf bank_mask:0xf bound_ctrl:1
	v_cndmask_b32_e64 v127, v120, v112, s[40:41]
	v_fmac_f32_dpp v162, v128, v156 row_ror:15 row_mask:0xf bank_mask:0xf bound_ctrl:1
;     __device__ __forceinline__ void operator()(const f32x4 (&acc)[2][2][4][2], const pg8::Unit& u, int wr, int wc, int fr, int fq) const {
;     ...
;             for (int n = 0; n < 2; ++n) {
;                 f32x4 wv[3], wg[3], bv, bg;
; #pragma unroll
;                 for (int k = 0; k < 3; ++k) { wv[k] = *(const f32x4*)(cw + k * 6144 + cv + 4 * n); wg[k] = *(const f32x4*)(cw + k * 6144 + DFF + cv + 4 * n); }
;                 bv = *(const f32x4*)(cbias + cv + 4 * n); bg = *(const f32x4*)(cbias + DFF + cv + 4 * n);
; #pragma unroll
;                 for (int ai = 0; ai < 2; ++ai) { const int s = 2 * ai + wr;
; #pragma unroll
;                     for (int m = 0; m < 4; ++m) {
;                         const int rl = 128 * ai + 64 * wr + 16 * m + fr, row = R0 + rl;
;                         f32x4 xpv, xpg, xnv, xng;
;                         if (m == 0) { const LAS float* p = xb + ((s > 0 ? s - 1 : 0) * 2 + 1) * 256 + cl + 4 * n; xpv = *(const LAS f32x4*)p; xpg = *(const LAS f32x4*)(p + 128); }
;                         if (m == 3) { const LAS float* p = xb + ((s < 3 ? s + 1 : 3) * 2 + 0) * 256 + cl + 4 * n; xnv = *(const LAS f32x4*)p; xng = *(const LAS f32x4*)(p + 128); }
;                         float o[4];
; #pragma unroll
;                         for (int e = 0; e < 4; ++e) {
;                             const float cvv = acc[ai][0][m][n][e], cgg = acc[ai][1][m][n][e];
;                             const float upv = m > 0 ? acc[ai][0][m > 0 ? m - 1 : 0][n][e] : xpv[e], upg = m > 0 ? acc[ai][1][m > 0 ? m - 1 : 0][n][e] : xpg[e];
;                             const float dnv = m < 3 ? acc[ai][0][m < 3 ? m + 1 : 3][n][e] : xnv[e], dng = m < 3 ? acc[ai][1][m < 3 ? m + 1 : 3][n][e] : xng[e];
;                             const float xpv_ = fr == 15 ? upv : cvv, xpg_ = fr == 15 ? upg : cgg;
;                             const float xnv_ = fr == 0 ? dnv : cvv, xng_ = fr == 0 ? dng : cgg;
;                             float val = bv[e] + wv[1][e] * cvv; val += wv[0][e] * dppf<0x121>(xpv_); val += wv[2][e] * dppf<0x12F>(xnv_);
;                             float gt = bg[e] + wg[1][e] * cgg; gt += wg[0][e] * dppf<0x121>(xpg_); gt += wg[2][e] * dppf<0x12F>(xng_);
;                             o[e] = val * gt * sigmoidf_(gt);
;                         }
;                         u32x2 ow; ow.x = pg8::cvt_pk_bf16(o[0], o[1]); ow.y = pg8::cvt_pk_bf16(o[2], o[3]);
	v_mul_f32_e32 v124, 0xbfb8aa3b, v162
	v_exp_f32_e32 v124, v124
	v_fma_f32 v128, v120, v140, v148
	v_fmac_f32_dpp v128, v126, v132 row_ror:1 row_mask:0xf bank_mask:0xf bound_ctrl:1
	v_add_f32_e32 v124, 1.0, v124
	v_rcp_f32_e32 v124, v124
	v_fmac_f32_dpp v128, v127, v136 row_ror:15 row_mask:0xf bank_mask:0xf bound_ctrl:1
	v_mul_f32_e32 v126, v128, v162
	v_cndmask_b32_e64 v125, v117, v125, s[42:43]
	v_mul_f32_e32 v124, v126, v124
	v_cndmask_b32_e64 v126, v121, v129, s[42:43]
	v_cndmask_b32_e64 v128, v117, v109, s[40:41]
	v_fma_f32 v129, v117, v161, v153
	v_fmac_f32_dpp v129, v125, v145 row_ror:1 row_mask:0xf bank_mask:0xf bound_ctrl:1
	v_cndmask_b32_e64 v127, v121, v113, s[40:41]
	v_fmac_f32_dpp v129, v128, v157 row_ror:15 row_mask:0xf bank_mask:0xf bound_ctrl:1
	v_mul_f32_e32 v125, 0xbfb8aa3b, v129
	v_exp_f32_e32 v125, v125
	v_fma_f32 v128, v121, v141, v149
	v_fmac_f32_dpp v128, v126, v133 row_ror:1 row_mask:0xf bank_mask:0xf bound_ctrl:1
	v_add_f32_e32 v125, 1.0, v125
	v_rcp_f32_e32 v125, v125
	v_fmac_f32_dpp v128, v127, v137 row_ror:15 row_mask:0xf bank_mask:0xf bound_ctrl:1
	v_add_u32_e32 v48, s39, v252
	v_mul_f32_e32 v126, v128, v129
	v_mul_f32_e32 v125, v126, v125
	v_cvt_pk_bf16_f32 v122, v122, v123
	v_cvt_pk_bf16_f32 v123, v124, v125
	s_nop 0
	v_mov_b32_e32 v206, v122
	v_mov_b32_e32 v207, v123
	v_cndmask_b32_e64 v114, v106, v114, s[42:43]
	v_cndmask_b32_e64 v124, v106, v98, s[40:41]
	v_fma_f32 v125, v106, v158, v150
	v_cndmask_b32_e64 v118, v110, v118, s[42:43]
	v_fmac_f32_dpp v125, v114, v142 row_ror:1 row_mask:0xf bank_mask:0xf bound_ctrl:1
	v_cndmask_b32_e64 v123, v110, v102, s[40:41]
	v_fmac_f32_dpp v125, v124, v154 row_ror:15 row_mask:0xf bank_mask:0xf bound_ctrl:1
	v_fma_f32 v124, v110, v138, v146
	v_mul_f32_e32 v114, 0xbfb8aa3b, v125
	v_fmac_f32_dpp v124, v118, v130 row_ror:1 row_mask:0xf bank_mask:0xf bound_ctrl:1
	v_exp_f32_e32 v114, v114
	v_fmac_f32_dpp v124, v123, v134 row_ror:15 row_mask:0xf bank_mask:0xf bound_ctrl:1
	v_cndmask_b32_e64 v115, v107, v115, s[42:43]
	v_mul_f32_e32 v118, v124, v125
	v_cndmask_b32_e64 v123, v107, v99, s[40:41]
	v_fma_f32 v124, v107, v159, v151
	v_fmac_f32_dpp v124, v115, v143 row_ror:1 row_mask:0xf bank_mask:0xf bound_ctrl:1
	v_add_f32_e32 v114, 1.0, v114
	v_fmac_f32_dpp v124, v123, v155 row_ror:15 row_mask:0xf bank_mask:0xf bound_ctrl:1
	v_mul_f32_e32 v115, 0xbfb8aa3b, v124
	v_rcp_f32_e32 v114, v114
	v_exp_f32_e32 v115, v115
	v_fma_f32 v123, v111, v139, v147
	v_cndmask_b32_e64 v116, v108, v116, s[42:43]
	v_mul_f32_e32 v114, v118, v114
	v_cndmask_b32_e64 v118, v111, v119, s[42:43]
	v_add_f32_e32 v115, 1.0, v115
	v_cndmask_b32_e64 v119, v111, v103, s[40:41]
	v_rcp_f32_e32 v115, v115
	v_fmac_f32_dpp v123, v118, v131 row_ror:1 row_mask:0xf bank_mask:0xf bound_ctrl:1
	v_fmac_f32_dpp v123, v119, v135 row_ror:15 row_mask:0xf bank_mask:0xf bound_ctrl:1
	v_mul_f32_e32 v118, v123, v124
	v_mul_f32_e32 v115, v118, v115
	v_cndmask_b32_e64 v118, v112, v120, s[42:43]
	v_cndmask_b32_e64 v120, v108, v100, s[40:41]
	v_fma_f32 v123, v108, v160, v152
	v_fmac_f32_dpp v123, v116, v144 row_ror:1 row_mask:0xf bank_mask:0xf bound_ctrl:1
	v_cndmask_b32_e64 v119, v112, v104, s[40:41]
	v_fmac_f32_dpp v123, v120, v156 row_ror:15 row_mask:0xf bank_mask:0xf bound_ctrl:1
	v_mul_f32_e32 v116, 0xbfb8aa3b, v123
	v_exp_f32_e32 v116, v116
	v_fma_f32 v120, v112, v140, v148
	v_fmac_f32_dpp v120, v118, v132 row_ror:1 row_mask:0xf bank_mask:0xf bound_ctrl:1
	v_add_f32_e32 v116, 1.0, v116
	v_rcp_f32_e32 v116, v116
	v_fmac_f32_dpp v120, v119, v136 row_ror:15 row_mask:0xf bank_mask:0xf bound_ctrl:1
	v_mul_f32_e32 v118, v120, v123
	v_cndmask_b32_e64 v117, v109, v117, s[42:43]
	v_mul_f32_e32 v116, v118, v116
	v_cndmask_b32_e64 v118, v113, v121, s[42:43]
	v_cndmask_b32_e64 v120, v109, v101, s[40:41]
	v_fma_f32 v121, v109, v161, v153
	v_fmac_f32_dpp v121, v117, v145 row_ror:1 row_mask:0xf bank_mask:0xf bound_ctrl:1
	v_cndmask_b32_e64 v119, v113, v105, s[40:41]
	v_fmac_f32_dpp v121, v120, v157 row_ror:15 row_mask:0xf bank_mask:0xf bound_ctrl:1
	v_mul_f32_e32 v117, 0xbfb8aa3b, v121
	v_exp_f32_e32 v117, v117
	v_fma_f32 v120, v113, v141, v149
	v_fmac_f32_dpp v120, v118, v133 row_ror:1 row_mask:0xf bank_mask:0xf bound_ctrl:1
	v_add_f32_e32 v117, 1.0, v117
	v_rcp_f32_e32 v117, v117
	v_fmac_f32_dpp v120, v119, v137 row_ror:15 row_mask:0xf bank_mask:0xf bound_ctrl:1
	v_add_u32_e32 v122, s39, v225
	v_mul_f32_e32 v118, v120, v121
	v_mul_f32_e32 v117, v118, v117
	v_cvt_pk_bf16_f32 v114, v114, v115
	v_cvt_pk_bf16_f32 v115, v116, v117
	s_nop 0
	v_mov_b32_e32 v208, v114
	v_mov_b32_e32 v209, v115
	ds_read_b128 v[116:119], v235 offset:2048
	ds_read_b128 v[124:127], v235 offset:2560
	v_cndmask_b32_e64 v106, v98, v106, s[42:43]
	v_cndmask_b32_e64 v110, v102, v110, s[42:43]
	v_add_u32_e32 v114, s39, v224
	s_waitcnt lgkmcnt(1)
	v_cndmask_b32_e64 v115, v102, v116, s[40:41]
	s_waitcnt lgkmcnt(0)
;     __device__ __forceinline__ void operator()(const f32x4 (&acc)[2][2][4][2], const pg8::Unit& u, int wr, int wc, int fr, int fq) const {
;     ...
;             for (int n = 0; n < 2; ++n) {
;                 f32x4 wv[3], wg[3], bv, bg;
; #pragma unroll
;                 for (int k = 0; k < 3; ++k) { wv[k] = *(const f32x4*)(cw + k * 6144 + cv + 4 * n); wg[k] = *(const f32x4*)(cw + k * 6144 + DFF + cv + 4 * n); }
;                 bv = *(const f32x4*)(cbias + cv + 4 * n); bg = *(const f32x4*)(cbias + DFF + cv + 4 * n);
; #pragma unroll
;                 for (int ai = 0; ai < 2; ++ai) { const int s = 2 * ai + wr;
; #pragma unroll
;                     for (int m = 0; m < 4; ++m) {
;                         const int rl = 128 * ai + 64 * wr + 16 * m + fr, row = R0 + rl;
;                         f32x4 xpv, xpg, xnv, xng;
;                         if (m == 0) { const LAS float* p = xb + ((s > 0 ? s - 1 : 0) * 2 + 1) * 256 + cl + 4 * n; xpv = *(const LAS f32x4*)p; xpg = *(const LAS f32x4*)(p + 128); }
;                         if (m == 3) { const LAS float* p = xb + ((s < 3 ? s + 1 : 3) * 2 + 0) * 256 + cl + 4 * n; xnv = *(const LAS f32x4*)p; xng = *(const LAS f32x4*)(p + 128); }
;                         float o[4];
; #pragma unroll
;                         for (int e = 0; e < 4; ++e) {
;                             const float cvv = acc[ai][0][m][n][e], cgg = acc[ai][1][m][n][e];
;                             const float upv = m > 0 ? acc[ai][0][m > 0 ? m - 1 : 0][n][e] : xpv[e], upg = m > 0 ? acc[ai][1][m > 0 ? m - 1 : 0][n][e] : xpg[e];
;                             const float dnv = m < 3 ? acc[ai][0][m < 3 ? m + 1 : 3][n][e] : xnv[e], dng = m < 3 ? acc[ai][1][m < 3 ? m + 1 : 3][n][e] : xng[e];
;                             const float xpv_ = fr == 15 ? upv : cvv, xpg_ = fr == 15 ? upg : cgg;
;                             const float xnv_ = fr == 0 ? dnv : cvv, xng_ = fr == 0 ? dng : cgg;
;                             float val = bv[e] + wv[1][e] * cvv; val += wv[0][e] * dppf<0x121>(xpv_); val += wv[2][e] * dppf<0x12F>(xnv_);
;                             float gt = bg[e] + wg[1][e] * cgg; gt += wg[0][e] * dppf<0x121>(xpg_); gt += wg[2][e] * dppf<0x12F>(xng_);
;                             o[e] = val * gt * sigmoidf_(gt);
;                         }
;                         u32x2 ow; ow.x = pg8::cvt_pk_bf16(o[0], o[1]); ow.y = pg8::cvt_pk_bf16(o[2], o[3]);
	v_cndmask_b32_e64 v116, v98, v124, s[40:41]
	v_fma_f32 v98, v98, v158, v150
	v_fmac_f32_dpp v98, v106, v142 row_ror:1 row_mask:0xf bank_mask:0xf bound_ctrl:1
	v_fma_f32 v102, v102, v138, v146
	v_fmac_f32_dpp v98, v116, v154 row_ror:15 row_mask:0xf bank_mask:0xf bound_ctrl:1
	v_mul_f32_e32 v106, 0xbfb8aa3b, v98
	v_exp_f32_e32 v106, v106
	v_fmac_f32_dpp v102, v110, v130 row_ror:1 row_mask:0xf bank_mask:0xf bound_ctrl:1
	v_add_f32_e32 v106, 1.0, v106
	v_rcp_f32_e32 v106, v106
	v_fmac_f32_dpp v102, v115, v134 row_ror:15 row_mask:0xf bank_mask:0xf bound_ctrl:1
	v_mul_f32_e32 v98, v102, v98
	v_mul_f32_e32 v98, v98, v106
	v_cndmask_b32_e64 v106, v99, v107, s[42:43]
	v_cndmask_b32_e64 v110, v99, v125, s[40:41]
	v_fma_f32 v99, v99, v159, v151
	v_fmac_f32_dpp v99, v106, v143 row_ror:1 row_mask:0xf bank_mask:0xf bound_ctrl:1
	v_cndmask_b32_e64 v102, v103, v111, s[42:43]
	v_fmac_f32_dpp v99, v110, v155 row_ror:15 row_mask:0xf bank_mask:0xf bound_ctrl:1
	v_mul_f32_e32 v106, 0xbfb8aa3b, v99
	v_exp_f32_e32 v106, v106
	v_cndmask_b32_e64 v107, v103, v117, s[40:41]
	v_fma_f32 v103, v103, v139, v147
	v_fmac_f32_dpp v103, v102, v131 row_ror:1 row_mask:0xf bank_mask:0xf bound_ctrl:1
	v_add_f32_e32 v102, 1.0, v106
	v_fmac_f32_dpp v103, v107, v135 row_ror:15 row_mask:0xf bank_mask:0xf bound_ctrl:1
	v_mul_f32_e32 v99, v103, v99
	v_cndmask_b32_e64 v103, v100, v108, s[42:43]
	v_cndmask_b32_e64 v107, v100, v126, s[40:41]
	v_fma_f32 v100, v100, v160, v152
	v_fmac_f32_dpp v100, v103, v144 row_ror:1 row_mask:0xf bank_mask:0xf bound_ctrl:1
	v_rcp_f32_e32 v102, v102
	v_fmac_f32_dpp v100, v107, v156 row_ror:15 row_mask:0xf bank_mask:0xf bound_ctrl:1
	v_mul_f32_e32 v103, 0xbfb8aa3b, v100
	v_exp_f32_e32 v103, v103
	v_mul_f32_e32 v99, v99, v102
	v_cndmask_b32_e64 v102, v104, v112, s[42:43]
	v_cndmask_b32_e64 v106, v104, v118, s[40:41]
	v_fma_f32 v104, v104, v140, v148
	v_fmac_f32_dpp v104, v102, v132 row_ror:1 row_mask:0xf bank_mask:0xf bound_ctrl:1
	v_add_f32_e32 v102, 1.0, v103
	v_fmac_f32_dpp v104, v106, v136 row_ror:15 row_mask:0xf bank_mask:0xf bound_ctrl:1
	v_cndmask_b32_e64 v103, v101, v109, s[42:43]
	v_cndmask_b32_e64 v106, v101, v127, s[40:41]
	v_fma_f32 v101, v101, v161, v153
	v_fmac_f32_dpp v101, v103, v145 row_ror:1 row_mask:0xf bank_mask:0xf bound_ctrl:1
	v_rcp_f32_e32 v102, v102
	v_fmac_f32_dpp v101, v106, v157 row_ror:15 row_mask:0xf bank_mask:0xf bound_ctrl:1
	v_mul_f32_e32 v103, 0xbfb8aa3b, v101
	v_exp_f32_e32 v103, v103
	v_mul_f32_e32 v100, v104, v100
	v_mul_f32_e32 v100, v100, v102
	v_cndmask_b32_e64 v102, v105, v113, s[42:43]
	v_cndmask_b32_e64 v104, v105, v119, s[40:41]
	v_fma_f32 v105, v105, v141, v149
	v_fmac_f32_dpp v105, v102, v133 row_ror:1 row_mask:0xf bank_mask:0xf bound_ctrl:1
	v_add_f32_e32 v102, 1.0, v103
	v_rcp_f32_e32 v102, v102
	v_fmac_f32_dpp v105, v104, v137 row_ror:15 row_mask:0xf bank_mask:0xf bound_ctrl:1
	v_mul_f32_e32 v101, v105, v101
	v_mul_f32_e32 v101, v101, v102
	v_cvt_pk_bf16_f32 v98, v98, v99
	v_cvt_pk_bf16_f32 v99, v100, v101
	s_nop 0
	v_mov_b32_e32 v210, v98
	v_mov_b32_e32 v211, v99
	ds_read_b128 v[98:101], v236
	ds_read_b128 v[102:105], v236 offset:512
	v_cndmask_b32_e64 v108, v90, v82, s[40:41]
	v_fma_f32 v109, v90, v158, v150
	v_cndmask_b32_e64 v107, v94, v86, s[40:41]
	s_waitcnt lgkmcnt(1)
	v_cndmask_b32_e64 v98, v94, v98, s[42:43]
	s_waitcnt lgkmcnt(0)
	v_cndmask_b32_e64 v102, v90, v102, s[42:43]
	v_cndmask_b32_e64 v99, v95, v99, s[42:43]
	s_nop 0
	v_fmac_f32_dpp v109, v102, v142 row_ror:1 row_mask:0xf bank_mask:0xf bound_ctrl:1
	v_fmac_f32_dpp v109, v108, v154 row_ror:15 row_mask:0xf bank_mask:0xf bound_ctrl:1
	v_mul_f32_e32 v102, 0xbfb8aa3b, v109
	v_exp_f32_e32 v102, v102
	v_fma_f32 v108, v94, v138, v146
	v_fmac_f32_dpp v108, v98, v130 row_ror:1 row_mask:0xf bank_mask:0xf bound_ctrl:1
	v_cndmask_b32_e64 v100, v96, v100, s[42:43]
	v_add_f32_e32 v98, 1.0, v102
	v_rcp_f32_e32 v98, v98
	v_fmac_f32_dpp v108, v107, v134 row_ror:15 row_mask:0xf bank_mask:0xf bound_ctrl:1
	v_mul_f32_e32 v102, v108, v109
	v_mul_f32_e32 v98, v102, v98
	v_cndmask_b32_e64 v102, v91, v103, s[42:43]
	v_cndmask_b32_e64 v107, v91, v83, s[40:41]
	v_fma_f32 v108, v91, v159, v151
	v_fmac_f32_dpp v108, v102, v143 row_ror:1 row_mask:0xf bank_mask:0xf bound_ctrl:1
	v_cndmask_b32_e64 v103, v95, v87, s[40:41]
	v_fmac_f32_dpp v108, v107, v155 row_ror:15 row_mask:0xf bank_mask:0xf bound_ctrl:1
	v_mul_f32_e32 v102, 0xbfb8aa3b, v108
	v_exp_f32_e32 v102, v102
	v_fma_f32 v107, v95, v139, v147
	v_fmac_f32_dpp v107, v99, v131 row_ror:1 row_mask:0xf bank_mask:0xf bound_ctrl:1
	v_add_f32_e32 v99, 1.0, v102
	v_rcp_f32_e32 v99, v99
	v_fmac_f32_dpp v107, v103, v135 row_ror:15 row_mask:0xf bank_mask:0xf bound_ctrl:1
	v_mul_f32_e32 v102, v107, v108
	v_mul_f32_e32 v99, v102, v99
	v_cndmask_b32_e64 v102, v92, v104, s[42:43]
	v_cndmask_b32_e64 v104, v92, v84, s[40:41]
	v_fma_f32 v107, v92, v160, v152
	v_fmac_f32_dpp v107, v102, v144 row_ror:1 row_mask:0xf bank_mask:0xf bound_ctrl:1
	v_cndmask_b32_e64 v103, v96, v88, s[40:41]
	v_fmac_f32_dpp v107, v104, v156 row_ror:15 row_mask:0xf bank_mask:0xf bound_ctrl:1
	v_mul_f32_e32 v102, 0xbfb8aa3b, v107
	v_exp_f32_e32 v102, v102
	v_fma_f32 v104, v96, v140, v148
	v_fmac_f32_dpp v104, v100, v132 row_ror:1 row_mask:0xf bank_mask:0xf bound_ctrl:1
	v_cndmask_b32_e64 v101, v97, v101, s[42:43]
	v_add_f32_e32 v100, 1.0, v102
	v_rcp_f32_e32 v100, v100
	v_fmac_f32_dpp v104, v103, v136 row_ror:15 row_mask:0xf bank_mask:0xf bound_ctrl:1
	v_mul_f32_e32 v102, v104, v107
	v_mul_f32_e32 v100, v102, v100
	v_cndmask_b32_e64 v102, v93, v105, s[42:43]
	v_cndmask_b32_e64 v104, v93, v85, s[40:41]
	v_fma_f32 v105, v93, v161, v153
;     __device__ __forceinline__ void operator()(const f32x4 (&acc)[2][2][4][2], const pg8::Unit& u, int wr, int wc, int fr, int fq) const {
;     ...
;             for (int n = 0; n < 2; ++n) {
;                 f32x4 wv[3], wg[3], bv, bg;
; #pragma unroll
;                 for (int k = 0; k < 3; ++k) { wv[k] = *(const f32x4*)(cw + k * 6144 + cv + 4 * n); wg[k] = *(const f32x4*)(cw + k * 6144 + DFF + cv + 4 * n); }
;                 bv = *(const f32x4*)(cbias + cv + 4 * n); bg = *(const f32x4*)(cbias + DFF + cv + 4 * n);
; #pragma unroll
;                 for (int ai = 0; ai < 2; ++ai) { const int s = 2 * ai + wr;
; #pragma unroll
;                     for (int m = 0; m < 4; ++m) {
;                         const int rl = 128 * ai + 64 * wr + 16 * m + fr, row = R0 + rl;
;                         f32x4 xpv, xpg, xnv, xng;
;                         if (m == 0) { const LAS float* p = xb + ((s > 0 ? s - 1 : 0) * 2 + 1) * 256 + cl + 4 * n; xpv = *(const LAS f32x4*)p; xpg = *(const LAS f32x4*)(p + 128); }
;                         if (m == 3) { const LAS float* p = xb + ((s < 3 ? s + 1 : 3) * 2 + 0) * 256 + cl + 4 * n; xnv = *(const LAS f32x4*)p; xng = *(const LAS f32x4*)(p + 128); }
;                         float o[4];
; #pragma unroll
;                         for (int e = 0; e < 4; ++e) {
;                             const float cvv = acc[ai][0][m][n][e], cgg = acc[ai][1][m][n][e];
;                             const float upv = m > 0 ? acc[ai][0][m > 0 ? m - 1 : 0][n][e] : xpv[e], upg = m > 0 ? acc[ai][1][m > 0 ? m - 1 : 0][n][e] : xpg[e];
;                             const float dnv = m < 3 ? acc[ai][0][m < 3 ? m + 1 : 3][n][e] : xnv[e], dng = m < 3 ? acc[ai][1][m < 3 ? m + 1 : 3][n][e] : xng[e];
;                             const float xpv_ = fr == 15 ? upv : cvv, xpg_ = fr == 15 ? upg : cgg;
;                             const float xnv_ = fr == 0 ? dnv : cvv, xng_ = fr == 0 ? dng : cgg;
;                             float val = bv[e] + wv[1][e] * cvv; val += wv[0][e] * dppf<0x121>(xpv_); val += wv[2][e] * dppf<0x12F>(xnv_);
;                             float gt = bg[e] + wg[1][e] * cgg; gt += wg[0][e] * dppf<0x121>(xpg_); gt += wg[2][e] * dppf<0x12F>(xng_);
;                             o[e] = val * gt * sigmoidf_(gt);
;                         }
;                         u32x2 ow; ow.x = pg8::cvt_pk_bf16(o[0], o[1]); ow.y = pg8::cvt_pk_bf16(o[2], o[3]);
	v_fmac_f32_dpp v105, v102, v145 row_ror:1 row_mask:0xf bank_mask:0xf bound_ctrl:1
	v_fmac_f32_dpp v105, v104, v157 row_ror:15 row_mask:0xf bank_mask:0xf bound_ctrl:1
	v_mul_f32_e32 v102, 0xbfb8aa3b, v105
	v_exp_f32_e32 v102, v102
	v_fma_f32 v104, v97, v141, v149
	v_fmac_f32_dpp v104, v101, v133 row_ror:1 row_mask:0xf bank_mask:0xf bound_ctrl:1
	v_cndmask_b32_e64 v103, v97, v89, s[40:41]
	v_add_f32_e32 v101, 1.0, v102
	v_rcp_f32_e32 v101, v101
	v_fmac_f32_dpp v104, v103, v137 row_ror:15 row_mask:0xf bank_mask:0xf bound_ctrl:1
	v_add_u32_e32 v106, s39, v221
	v_mul_f32_e32 v102, v104, v105
	v_mul_f32_e32 v101, v102, v101
	v_cvt_pk_bf16_f32 v98, v98, v99
	v_cvt_pk_bf16_f32 v99, v100, v101
	s_nop 0
	v_mov_b32_e32 v212, v98
	v_mov_b32_e32 v213, v99
	v_cndmask_b32_e64 v90, v82, v90, s[42:43]
	v_cndmask_b32_e64 v99, v82, v74, s[40:41]
	v_fma_f32 v100, v82, v158, v150
	v_cndmask_b32_e64 v94, v86, v94, s[42:43]
	v_fmac_f32_dpp v100, v90, v142 row_ror:1 row_mask:0xf bank_mask:0xf bound_ctrl:1
	v_cndmask_b32_e64 v98, v86, v78, s[40:41]
	v_fmac_f32_dpp v100, v99, v154 row_ror:15 row_mask:0xf bank_mask:0xf bound_ctrl:1
	v_fma_f32 v99, v86, v138, v146
	v_mul_f32_e32 v90, 0xbfb8aa3b, v100
	v_fmac_f32_dpp v99, v94, v130 row_ror:1 row_mask:0xf bank_mask:0xf bound_ctrl:1
	v_exp_f32_e32 v90, v90
	v_fmac_f32_dpp v99, v98, v134 row_ror:15 row_mask:0xf bank_mask:0xf bound_ctrl:1
	v_cndmask_b32_e64 v91, v83, v91, s[42:43]
	v_mul_f32_e32 v94, v99, v100
	v_cndmask_b32_e64 v98, v83, v75, s[40:41]
	v_fma_f32 v99, v83, v159, v151
	v_fmac_f32_dpp v99, v91, v143 row_ror:1 row_mask:0xf bank_mask:0xf bound_ctrl:1
	v_add_f32_e32 v90, 1.0, v90
	v_fmac_f32_dpp v99, v98, v155 row_ror:15 row_mask:0xf bank_mask:0xf bound_ctrl:1
	v_mul_f32_e32 v91, 0xbfb8aa3b, v99
	v_rcp_f32_e32 v90, v90
	v_exp_f32_e32 v91, v91
	v_fma_f32 v98, v87, v139, v147
	v_cndmask_b32_e64 v92, v84, v92, s[42:43]
	v_mul_f32_e32 v90, v94, v90
	v_cndmask_b32_e64 v94, v87, v95, s[42:43]
	v_add_f32_e32 v91, 1.0, v91
	v_cndmask_b32_e64 v95, v87, v79, s[40:41]
	v_rcp_f32_e32 v91, v91
	v_fmac_f32_dpp v98, v94, v131 row_ror:1 row_mask:0xf bank_mask:0xf bound_ctrl:1
	v_fmac_f32_dpp v98, v95, v135 row_ror:15 row_mask:0xf bank_mask:0xf bound_ctrl:1
	v_mul_f32_e32 v94, v98, v99
	v_mul_f32_e32 v91, v94, v91
	v_cndmask_b32_e64 v94, v88, v96, s[42:43]
	v_cndmask_b32_e64 v96, v84, v76, s[40:41]
	v_fma_f32 v98, v84, v160, v152
	v_fmac_f32_dpp v98, v92, v144 row_ror:1 row_mask:0xf bank_mask:0xf bound_ctrl:1
	v_cndmask_b32_e64 v95, v88, v80, s[40:41]
	v_fmac_f32_dpp v98, v96, v156 row_ror:15 row_mask:0xf bank_mask:0xf bound_ctrl:1
	v_mul_f32_e32 v92, 0xbfb8aa3b, v98
	v_exp_f32_e32 v92, v92
	v_fma_f32 v96, v88, v140, v148
	v_fmac_f32_dpp v96, v94, v132 row_ror:1 row_mask:0xf bank_mask:0xf bound_ctrl:1
	v_add_f32_e32 v92, 1.0, v92
	v_rcp_f32_e32 v92, v92
	v_fmac_f32_dpp v96, v95, v136 row_ror:15 row_mask:0xf bank_mask:0xf bound_ctrl:1
	v_mul_f32_e32 v94, v96, v98
	v_cndmask_b32_e64 v93, v85, v93, s[42:43]
	v_mul_f32_e32 v92, v94, v92
	v_cndmask_b32_e64 v94, v89, v97, s[42:43]
	v_cndmask_b32_e64 v96, v85, v77, s[40:41]
	v_fma_f32 v97, v85, v161, v153
	v_fmac_f32_dpp v97, v93, v145 row_ror:1 row_mask:0xf bank_mask:0xf bound_ctrl:1
	v_cndmask_b32_e64 v95, v89, v81, s[40:41]
	v_fmac_f32_dpp v97, v96, v157 row_ror:15 row_mask:0xf bank_mask:0xf bound_ctrl:1
	v_mul_f32_e32 v93, 0xbfb8aa3b, v97
	v_exp_f32_e32 v93, v93
	v_fma_f32 v96, v89, v141, v149
	v_fmac_f32_dpp v96, v94, v133 row_ror:1 row_mask:0xf bank_mask:0xf bound_ctrl:1
	v_add_f32_e32 v93, 1.0, v93
	v_rcp_f32_e32 v93, v93
	v_fmac_f32_dpp v96, v95, v137 row_ror:15 row_mask:0xf bank_mask:0xf bound_ctrl:1
	v_add_u32_e32 v108, s39, v228
	v_mul_f32_e32 v94, v96, v97
	v_mul_f32_e32 v93, v94, v93
	v_cvt_pk_bf16_f32 v90, v90, v91
	v_cvt_pk_bf16_f32 v91, v92, v93
	s_nop 0
	v_mov_b32_e32 v214, v90
	v_mov_b32_e32 v215, v91
	v_cndmask_b32_e64 v82, v74, v82, s[42:43]
	v_cndmask_b32_e64 v91, v74, v66, s[40:41]
	v_fma_f32 v92, v74, v158, v150
	v_cndmask_b32_e64 v86, v78, v86, s[42:43]
	v_fmac_f32_dpp v92, v82, v142 row_ror:1 row_mask:0xf bank_mask:0xf bound_ctrl:1
	v_cndmask_b32_e64 v90, v78, v70, s[40:41]
	v_fmac_f32_dpp v92, v91, v154 row_ror:15 row_mask:0xf bank_mask:0xf bound_ctrl:1
	v_fma_f32 v91, v78, v138, v146
	v_mul_f32_e32 v82, 0xbfb8aa3b, v92
	v_fmac_f32_dpp v91, v86, v130 row_ror:1 row_mask:0xf bank_mask:0xf bound_ctrl:1
	v_exp_f32_e32 v82, v82
	v_fmac_f32_dpp v91, v90, v134 row_ror:15 row_mask:0xf bank_mask:0xf bound_ctrl:1
	v_cndmask_b32_e64 v83, v75, v83, s[42:43]
	v_mul_f32_e32 v86, v91, v92
	v_cndmask_b32_e64 v90, v75, v67, s[40:41]
	v_fma_f32 v91, v75, v159, v151
	v_fmac_f32_dpp v91, v83, v143 row_ror:1 row_mask:0xf bank_mask:0xf bound_ctrl:1
	v_add_f32_e32 v82, 1.0, v82
	v_fmac_f32_dpp v91, v90, v155 row_ror:15 row_mask:0xf bank_mask:0xf bound_ctrl:1
	v_mul_f32_e32 v83, 0xbfb8aa3b, v91
	v_rcp_f32_e32 v82, v82
	v_exp_f32_e32 v83, v83
	v_fma_f32 v90, v79, v139, v147
	v_cndmask_b32_e64 v84, v76, v84, s[42:43]
	v_mul_f32_e32 v82, v86, v82
	v_cndmask_b32_e64 v86, v79, v87, s[42:43]
	v_add_f32_e32 v83, 1.0, v83
	v_cndmask_b32_e64 v87, v79, v71, s[40:41]
	v_rcp_f32_e32 v83, v83
	v_fmac_f32_dpp v90, v86, v131 row_ror:1 row_mask:0xf bank_mask:0xf bound_ctrl:1
	v_fmac_f32_dpp v90, v87, v135 row_ror:15 row_mask:0xf bank_mask:0xf bound_ctrl:1
	v_mul_f32_e32 v86, v90, v91
	v_mul_f32_e32 v83, v86, v83
	v_cndmask_b32_e64 v86, v80, v88, s[42:43]
	v_cndmask_b32_e64 v88, v76, v68, s[40:41]
	v_fma_f32 v90, v76, v160, v152
	v_fmac_f32_dpp v90, v84, v144 row_ror:1 row_mask:0xf bank_mask:0xf bound_ctrl:1
	v_cndmask_b32_e64 v87, v80, v72, s[40:41]
	v_fmac_f32_dpp v90, v88, v156 row_ror:15 row_mask:0xf bank_mask:0xf bound_ctrl:1
;     __device__ __forceinline__ void operator()(const f32x4 (&acc)[2][2][4][2], const pg8::Unit& u, int wr, int wc, int fr, int fq) const {
;     ...
;             for (int n = 0; n < 2; ++n) {
;                 f32x4 wv[3], wg[3], bv, bg;
; #pragma unroll
;                 for (int k = 0; k < 3; ++k) { wv[k] = *(const f32x4*)(cw + k * 6144 + cv + 4 * n); wg[k] = *(const f32x4*)(cw + k * 6144 + DFF + cv + 4 * n); }
;                 bv = *(const f32x4*)(cbias + cv + 4 * n); bg = *(const f32x4*)(cbias + DFF + cv + 4 * n);
; #pragma unroll
;                 for (int ai = 0; ai < 2; ++ai) { const int s = 2 * ai + wr;
; #pragma unroll
;                     for (int m = 0; m < 4; ++m) {
;                         const int rl = 128 * ai + 64 * wr + 16 * m + fr, row = R0 + rl;
;                         f32x4 xpv, xpg, xnv, xng;
;                         if (m == 0) { const LAS float* p = xb + ((s > 0 ? s - 1 : 0) * 2 + 1) * 256 + cl + 4 * n; xpv = *(const LAS f32x4*)p; xpg = *(const LAS f32x4*)(p + 128); }
;                         if (m == 3) { const LAS float* p = xb + ((s < 3 ? s + 1 : 3) * 2 + 0) * 256 + cl + 4 * n; xnv = *(const LAS f32x4*)p; xng = *(const LAS f32x4*)(p + 128); }
;                         float o[4];
; #pragma unroll
;                         for (int e = 0; e < 4; ++e) {
;                             const float cvv = acc[ai][0][m][n][e], cgg = acc[ai][1][m][n][e];
;                             const float upv = m > 0 ? acc[ai][0][m > 0 ? m - 1 : 0][n][e] : xpv[e], upg = m > 0 ? acc[ai][1][m > 0 ? m - 1 : 0][n][e] : xpg[e];
;                             const float dnv = m < 3 ? acc[ai][0][m < 3 ? m + 1 : 3][n][e] : xnv[e], dng = m < 3 ? acc[ai][1][m < 3 ? m + 1 : 3][n][e] : xng[e];
;                             const float xpv_ = fr == 15 ? upv : cvv, xpg_ = fr == 15 ? upg : cgg;
;                             const float xnv_ = fr == 0 ? dnv : cvv, xng_ = fr == 0 ? dng : cgg;
;                             float val = bv[e] + wv[1][e] * cvv; val += wv[0][e] * dppf<0x121>(xpv_); val += wv[2][e] * dppf<0x12F>(xnv_);
;                             float gt = bg[e] + wg[1][e] * cgg; gt += wg[0][e] * dppf<0x121>(xpg_); gt += wg[2][e] * dppf<0x12F>(xng_);
;                             o[e] = val * gt * sigmoidf_(gt);
;                         }
;                         u32x2 ow; ow.x = pg8::cvt_pk_bf16(o[0], o[1]); ow.y = pg8::cvt_pk_bf16(o[2], o[3]);
	v_mul_f32_e32 v84, 0xbfb8aa3b, v90
	v_exp_f32_e32 v84, v84
	v_fma_f32 v88, v80, v140, v148
	v_fmac_f32_dpp v88, v86, v132 row_ror:1 row_mask:0xf bank_mask:0xf bound_ctrl:1
	v_add_f32_e32 v84, 1.0, v84
	v_rcp_f32_e32 v84, v84
	v_fmac_f32_dpp v88, v87, v136 row_ror:15 row_mask:0xf bank_mask:0xf bound_ctrl:1
	v_mul_f32_e32 v86, v88, v90
	v_cndmask_b32_e64 v85, v77, v85, s[42:43]
	v_mul_f32_e32 v84, v86, v84
	v_cndmask_b32_e64 v86, v81, v89, s[42:43]
	v_cndmask_b32_e64 v88, v77, v69, s[40:41]
	v_fma_f32 v89, v77, v161, v153
	v_fmac_f32_dpp v89, v85, v145 row_ror:1 row_mask:0xf bank_mask:0xf bound_ctrl:1
	v_cndmask_b32_e64 v87, v81, v73, s[40:41]
	v_fmac_f32_dpp v89, v88, v157 row_ror:15 row_mask:0xf bank_mask:0xf bound_ctrl:1
	v_mul_f32_e32 v85, 0xbfb8aa3b, v89
	v_exp_f32_e32 v85, v85
	v_fma_f32 v88, v81, v141, v149
	v_fmac_f32_dpp v88, v86, v133 row_ror:1 row_mask:0xf bank_mask:0xf bound_ctrl:1
	v_add_f32_e32 v85, 1.0, v85
	v_rcp_f32_e32 v85, v85
	v_fmac_f32_dpp v88, v87, v137 row_ror:15 row_mask:0xf bank_mask:0xf bound_ctrl:1
	v_add_u32_e32 v109, s39, v229
	v_mul_f32_e32 v86, v88, v89
	v_mul_f32_e32 v85, v86, v85
	v_cvt_pk_bf16_f32 v82, v82, v83
	v_cvt_pk_bf16_f32 v83, v84, v85
	s_nop 0
	v_mov_b32_e32 v216, v82
	v_mov_b32_e32 v217, v83
	ds_read_b128 v[82:85], v237 offset:2048
	ds_read_b128 v[86:89], v237 offset:2560
	v_cndmask_b32_e64 v74, v66, v74, s[42:43]
	v_cndmask_b32_e64 v78, v70, v78, s[42:43]
	v_fmac_f32_e32 v153, v69, v161
	s_waitcnt lgkmcnt(0)
	v_cndmask_b32_e64 v86, v66, v86, s[40:41]
	v_fma_f32 v66, v66, v158, v150
	v_fmac_f32_dpp v66, v74, v142 row_ror:1 row_mask:0xf bank_mask:0xf bound_ctrl:1
	v_fmac_f32_dpp v66, v86, v154 row_ror:15 row_mask:0xf bank_mask:0xf bound_ctrl:1
	v_mul_f32_e32 v74, 0xbfb8aa3b, v66
	v_exp_f32_e32 v74, v74
	v_cndmask_b32_e64 v82, v70, v82, s[40:41]
	v_fma_f32 v70, v70, v138, v146
	v_add_f32_e32 v74, 1.0, v74
	v_rcp_f32_e32 v74, v74
	v_fmac_f32_dpp v70, v78, v130 row_ror:1 row_mask:0xf bank_mask:0xf bound_ctrl:1
	v_fmac_f32_dpp v70, v82, v134 row_ror:15 row_mask:0xf bank_mask:0xf bound_ctrl:1
	v_mul_f32_e32 v66, v70, v66
	v_mul_f32_e32 v66, v66, v74
	v_cndmask_b32_e64 v74, v67, v75, s[42:43]
	v_cndmask_b32_e64 v78, v67, v87, s[40:41]
	v_fma_f32 v67, v67, v159, v151
	v_fmac_f32_dpp v67, v74, v143 row_ror:1 row_mask:0xf bank_mask:0xf bound_ctrl:1
	v_cndmask_b32_e64 v70, v71, v79, s[42:43]
	v_fmac_f32_dpp v67, v78, v155 row_ror:15 row_mask:0xf bank_mask:0xf bound_ctrl:1
	v_mul_f32_e32 v74, 0xbfb8aa3b, v67
	v_exp_f32_e32 v74, v74
	v_cndmask_b32_e64 v75, v71, v83, s[40:41]
	v_fma_f32 v71, v71, v139, v147
	v_fmac_f32_dpp v71, v70, v131 row_ror:1 row_mask:0xf bank_mask:0xf bound_ctrl:1
	v_add_f32_e32 v70, 1.0, v74
	v_fmac_f32_dpp v71, v75, v135 row_ror:15 row_mask:0xf bank_mask:0xf bound_ctrl:1
	v_mul_f32_e32 v67, v71, v67
	v_cndmask_b32_e64 v71, v68, v76, s[42:43]
	v_cndmask_b32_e64 v75, v68, v88, s[40:41]
	v_fma_f32 v68, v68, v160, v152
	v_fmac_f32_dpp v68, v71, v144 row_ror:1 row_mask:0xf bank_mask:0xf bound_ctrl:1
	v_rcp_f32_e32 v70, v70
	v_fmac_f32_dpp v68, v75, v156 row_ror:15 row_mask:0xf bank_mask:0xf bound_ctrl:1
	v_mul_f32_e32 v71, 0xbfb8aa3b, v68
	v_exp_f32_e32 v71, v71
	v_mul_f32_e32 v67, v67, v70
	v_cndmask_b32_e64 v70, v72, v80, s[42:43]
	v_cndmask_b32_e64 v74, v72, v84, s[40:41]
	v_fma_f32 v72, v72, v140, v148
	v_fmac_f32_dpp v72, v70, v132 row_ror:1 row_mask:0xf bank_mask:0xf bound_ctrl:1
	v_add_f32_e32 v70, 1.0, v71
	v_fmac_f32_dpp v72, v74, v136 row_ror:15 row_mask:0xf bank_mask:0xf bound_ctrl:1
	v_cndmask_b32_e64 v71, v69, v77, s[42:43]
	v_cndmask_b32_e64 v74, v69, v89, s[40:41]
	v_rcp_f32_e32 v70, v70
	v_fmac_f32_dpp v153, v71, v145 row_ror:1 row_mask:0xf bank_mask:0xf bound_ctrl:1
	v_mul_f32_e32 v68, v72, v68
	v_fmac_f32_dpp v153, v74, v157 row_ror:15 row_mask:0xf bank_mask:0xf bound_ctrl:1
	v_mul_f32_e32 v69, 0xbfb8aa3b, v153
	v_exp_f32_e32 v69, v69
	v_mul_f32_e32 v68, v68, v70
	v_cndmask_b32_e64 v70, v73, v81, s[42:43]
	v_cndmask_b32_e64 v72, v73, v85, s[40:41]
	v_add_f32_e32 v69, 1.0, v69
	v_fmac_f32_e32 v149, v73, v141
	v_rcp_f32_e32 v69, v69
	v_fmac_f32_dpp v149, v70, v133 row_ror:1 row_mask:0xf bank_mask:0xf bound_ctrl:1
	v_fmac_f32_dpp v149, v72, v137 row_ror:15 row_mask:0xf bank_mask:0xf bound_ctrl:1
	v_add_u32_e32 v107, s39, v230
	v_mul_f32_e32 v70, v149, v153
	v_mul_f32_e32 v69, v70, v69
	v_cvt_pk_bf16_f32 v66, v66, v67
	v_cvt_pk_bf16_f32 v67, v68, v69
	s_nop 0
	v_mov_b32_e32 v218, v66
	v_mov_b32_e32 v219, v67
	v_add_co_u32_e32 v70, vcc, 0x3000, v190
	s_mov_b32 s2, 0xc000
	s_nop 0
	v_addc_co_u32_e32 v71, vcc, 0, v191, vcc
	v_add_co_u32_e32 v74, vcc, 0x6000, v190
	global_load_dwordx4 v[66:69], v[190:191], off offset:16
	s_nop 0
	v_addc_co_u32_e32 v75, vcc, 0, v191, vcc
	v_add_co_u32_e32 v78, vcc, 0x9000, v190
	global_load_dwordx4 v[70:73], v[70:71], off offset:16
	s_nop 0
	v_addc_co_u32_e32 v79, vcc, 0, v191, vcc
	global_load_dwordx4 v[82:85], v[78:79], off offset:16
	v_add_co_u32_e32 v78, vcc, s2, v190
	s_mov_b32 s2, 0xf000
	s_nop 0
	v_addc_co_u32_e32 v79, vcc, 0, v191, vcc
	v_add_co_u32_e32 v86, vcc, s2, v190
	s_movk_i32 s2, 0x3000
	s_nop 0
	v_addc_co_u32_e32 v87, vcc, 0, v191, vcc
	global_load_dwordx4 v[74:77], v[74:75], off offset:16
	v_add_co_u32_e32 v94, vcc, s2, v192
	global_load_dwordx4 v[78:81], v[78:79], off offset:16
	s_nop 0
	global_load_dwordx4 v[86:89], v[86:87], off offset:16
	s_nop 0
	global_load_dwordx4 v[90:93], v[192:193], off offset:16
	v_addc_co_u32_e32 v95, vcc, 0, v193, vcc
	global_load_dwordx4 v[94:97], v[94:95], off offset:16
	ds_read_b128 v[102:105], v238
	ds_read_b128 v[98:101], v239
	v_cndmask_b32_e64 v110, v62, v54, s[40:41]
	v_cndmask_b32_e64 v111, v58, v50, s[40:41]
	s_waitcnt lgkmcnt(1)
;     __device__ __forceinline__ void operator()(const f32x4 (&acc)[2][2][4][2], const pg8::Unit& u, int wr, int wc, int fr, int fq) const {
;     ...
;             for (int n = 0; n < 2; ++n) {
;                 f32x4 wv[3], wg[3], bv, bg;
; #pragma unroll
;                 for (int k = 0; k < 3; ++k) { wv[k] = *(const f32x4*)(cw + k * 6144 + cv + 4 * n); wg[k] = *(const f32x4*)(cw + k * 6144 + DFF + cv + 4 * n); }
;                 bv = *(const f32x4*)(cbias + cv + 4 * n); bg = *(const f32x4*)(cbias + DFF + cv + 4 * n);
; #pragma unroll
;                 for (int ai = 0; ai < 2; ++ai) { const int s = 2 * ai + wr;
; #pragma unroll
;                     for (int m = 0; m < 4; ++m) {
;                         const int rl = 128 * ai + 64 * wr + 16 * m + fr, row = R0 + rl;
;                         f32x4 xpv, xpg, xnv, xng;
;                         if (m == 0) { const LAS float* p = xb + ((s > 0 ? s - 1 : 0) * 2 + 1) * 256 + cl + 4 * n; xpv = *(const LAS f32x4*)p; xpg = *(const LAS f32x4*)(p + 128); }
;                         if (m == 3) { const LAS float* p = xb + ((s < 3 ? s + 1 : 3) * 2 + 0) * 256 + cl + 4 * n; xnv = *(const LAS f32x4*)p; xng = *(const LAS f32x4*)(p + 128); }
;                         float o[4];
; #pragma unroll
;                         for (int e = 0; e < 4; ++e) {
;                             const float cvv = acc[ai][0][m][n][e], cgg = acc[ai][1][m][n][e];
;                             const float upv = m > 0 ? acc[ai][0][m > 0 ? m - 1 : 0][n][e] : xpv[e], upg = m > 0 ? acc[ai][1][m > 0 ? m - 1 : 0][n][e] : xpg[e];
;                             const float dnv = m < 3 ? acc[ai][0][m < 3 ? m + 1 : 3][n][e] : xnv[e], dng = m < 3 ? acc[ai][1][m < 3 ? m + 1 : 3][n][e] : xng[e];
;                             const float xpv_ = fr == 15 ? upv : cvv, xpg_ = fr == 15 ? upg : cgg;
;                             const float xnv_ = fr == 0 ? dnv : cvv, xng_ = fr == 0 ? dng : cgg;
;                             float val = bv[e] + wv[1][e] * cvv; val += wv[0][e] * dppf<0x121>(xpv_); val += wv[2][e] * dppf<0x12F>(xnv_);
;                             float gt = bg[e] + wg[1][e] * cgg; gt += wg[0][e] * dppf<0x121>(xpg_); gt += wg[2][e] * dppf<0x12F>(xng_);
;                             o[e] = val * gt * sigmoidf_(gt);
;                         }
;                         u32x2 ow; ow.x = pg8::cvt_pk_bf16(o[0], o[1]); ow.y = pg8::cvt_pk_bf16(o[2], o[3]);
	v_cndmask_b32_e64 v102, v62, v102, s[42:43]
	s_waitcnt lgkmcnt(0)
	v_cndmask_b32_e64 v98, v58, v98, s[42:43]
	v_cndmask_b32_e64 v99, v59, v99, s[42:43]
	v_cndmask_b32_e64 v100, v60, v100, s[42:43]
	v_cndmask_b32_e64 v101, v61, v101, s[42:43]
	s_waitcnt vmcnt(1)
	v_fma_f32 v112, v62, v74, v90
	v_fmac_f32_dpp v112, v102, v66 row_ror:1 row_mask:0xf bank_mask:0xf bound_ctrl:1
	v_fmac_f32_dpp v112, v110, v78 row_ror:15 row_mask:0xf bank_mask:0xf bound_ctrl:1
	s_waitcnt vmcnt(0)
	v_fma_f32 v102, v58, v82, v94
	v_fmac_f32_dpp v102, v98, v70 row_ror:1 row_mask:0xf bank_mask:0xf bound_ctrl:1
	v_fmac_f32_dpp v102, v111, v86 row_ror:15 row_mask:0xf bank_mask:0xf bound_ctrl:1
	v_mul_f32_e32 v98, v112, v102
	v_mul_f32_e32 v102, 0xbfb8aa3b, v102
	v_exp_f32_e32 v102, v102
	v_fma_f32 v111, v63, v75, v91
	v_cndmask_b32_e64 v110, v59, v51, s[40:41]
	v_add_f32_e32 v102, 1.0, v102
	v_rcp_f32_e32 v102, v102
	s_nop 0
	v_mul_f32_e32 v98, v98, v102
	v_cndmask_b32_e64 v102, v63, v103, s[42:43]
	v_cndmask_b32_e64 v103, v63, v55, s[40:41]
	s_nop 0
	v_fmac_f32_dpp v111, v102, v67 row_ror:1 row_mask:0xf bank_mask:0xf bound_ctrl:1
	s_nop 0
	v_fmac_f32_dpp v111, v103, v79 row_ror:15 row_mask:0xf bank_mask:0xf bound_ctrl:1
	v_fma_f32 v102, v59, v83, v95
	v_fmac_f32_dpp v102, v99, v71 row_ror:1 row_mask:0xf bank_mask:0xf bound_ctrl:1
	v_fmac_f32_dpp v102, v110, v87 row_ror:15 row_mask:0xf bank_mask:0xf bound_ctrl:1
	v_mul_f32_e32 v99, v111, v102
	v_mul_f32_e32 v102, 0xbfb8aa3b, v102
	v_exp_f32_e32 v102, v102
	v_cndmask_b32_e64 v103, v64, v56, s[40:41]
	v_fma_f32 v110, v64, v76, v92
	v_add_f32_e32 v102, 1.0, v102
	v_rcp_f32_e32 v102, v102
	s_nop 0
	v_mul_f32_e32 v99, v99, v102
	v_cndmask_b32_e64 v102, v64, v104, s[42:43]
	v_cndmask_b32_e64 v104, v60, v52, s[40:41]
	v_cvt_pk_bf16_f32 v98, v98, v99
	s_nop 0
	v_fmac_f32_dpp v110, v102, v68 row_ror:1 row_mask:0xf bank_mask:0xf bound_ctrl:1
	s_nop 0
	v_fmac_f32_dpp v110, v103, v80 row_ror:15 row_mask:0xf bank_mask:0xf bound_ctrl:1
	v_fma_f32 v102, v60, v84, v96
	v_fmac_f32_dpp v102, v100, v72 row_ror:1 row_mask:0xf bank_mask:0xf bound_ctrl:1
	v_fmac_f32_dpp v102, v104, v88 row_ror:15 row_mask:0xf bank_mask:0xf bound_ctrl:1
	v_mul_f32_e32 v100, v110, v102
	v_mul_f32_e32 v102, 0xbfb8aa3b, v102
	v_exp_f32_e32 v102, v102
	v_cndmask_b32_e64 v103, v65, v57, s[40:41]
	v_cndmask_b32_e64 v104, v61, v53, s[40:41]
	v_add_f32_e32 v102, 1.0, v102
	v_rcp_f32_e32 v102, v102
	s_nop 0
	v_mul_f32_e32 v100, v100, v102
	v_cndmask_b32_e64 v102, v65, v105, s[42:43]
	v_fma_f32 v105, v65, v77, v93
	s_nop 0
	v_fmac_f32_dpp v105, v102, v69 row_ror:1 row_mask:0xf bank_mask:0xf bound_ctrl:1
	s_nop 0
	v_fmac_f32_dpp v105, v103, v81 row_ror:15 row_mask:0xf bank_mask:0xf bound_ctrl:1
	v_fma_f32 v102, v61, v85, v97
	v_fmac_f32_dpp v102, v101, v73 row_ror:1 row_mask:0xf bank_mask:0xf bound_ctrl:1
	v_fmac_f32_dpp v102, v104, v89 row_ror:15 row_mask:0xf bank_mask:0xf bound_ctrl:1
	v_mul_f32_e32 v101, v105, v102
	v_mul_f32_e32 v102, 0xbfb8aa3b, v102
	v_exp_f32_e32 v102, v102
	s_nop 0
	v_add_f32_e32 v102, 1.0, v102
	v_rcp_f32_e32 v102, v102
	s_nop 0
	v_mul_f32_e32 v101, v101, v102
	v_cvt_pk_bf16_f32 v99, v100, v101
	s_nop 0
	v_mov_b32_e32 v116, v172
	v_mov_b32_e32 v117, v173
	v_mov_b32_e32 v118, v98
	v_mov_b32_e32 v119, v99
	s_and_saveexec_b64 s[2:3], s[44:45]
	s_cbranch_execz .LBB0_452
	v_mov_b64_e32 v[100:101], s[20:21]
	s_movk_i32 s6, 0x1800
	v_mad_i64_i32 v[100:101], s[6:7], v243, s6, v[100:101]
	v_lshl_add_u64 v[100:101], v[188:189], 1, v[100:101]
	global_store_dwordx4 v[100:101], v[116:119], off
.LBB0_452:
	s_or_b64 exec, exec, s[2:3]
	v_cndmask_b32_e64 v58, v50, v58, s[42:43]
	v_cndmask_b32_e64 v99, v50, v40, s[40:41]
	v_fma_f32 v100, v50, v82, v94
	v_cndmask_b32_e64 v62, v54, v62, s[42:43]
	v_fmac_f32_dpp v100, v58, v70 row_ror:1 row_mask:0xf bank_mask:0xf bound_ctrl:1
	v_cndmask_b32_e64 v98, v54, v44, s[40:41]
	v_fmac_f32_dpp v100, v99, v86 row_ror:15 row_mask:0xf bank_mask:0xf bound_ctrl:1
	v_fma_f32 v99, v54, v74, v90
	v_mul_f32_e32 v58, 0xbfb8aa3b, v100
	v_fmac_f32_dpp v99, v62, v66 row_ror:1 row_mask:0xf bank_mask:0xf bound_ctrl:1
	v_exp_f32_e32 v58, v58
	v_fmac_f32_dpp v99, v98, v78 row_ror:15 row_mask:0xf bank_mask:0xf bound_ctrl:1
	v_cndmask_b32_e64 v59, v51, v59, s[42:43]
	v_mul_f32_e32 v62, v99, v100
	v_cndmask_b32_e64 v98, v51, v41, s[40:41]
	v_fma_f32 v99, v51, v83, v95
	v_fmac_f32_dpp v99, v59, v71 row_ror:1 row_mask:0xf bank_mask:0xf bound_ctrl:1
	v_add_f32_e32 v58, 1.0, v58
	v_fmac_f32_dpp v99, v98, v87 row_ror:15 row_mask:0xf bank_mask:0xf bound_ctrl:1
	v_mul_f32_e32 v59, 0xbfb8aa3b, v99
	v_rcp_f32_e32 v58, v58
	v_exp_f32_e32 v59, v59
	v_fma_f32 v98, v55, v75, v91
	v_cndmask_b32_e64 v60, v52, v60, s[42:43]
	v_mul_f32_e32 v58, v62, v58
	v_cndmask_b32_e64 v62, v55, v63, s[42:43]
	v_add_f32_e32 v59, 1.0, v59
	v_cndmask_b32_e64 v63, v55, v45, s[40:41]
	v_rcp_f32_e32 v59, v59
	v_fmac_f32_dpp v98, v62, v67 row_ror:1 row_mask:0xf bank_mask:0xf bound_ctrl:1
	v_fmac_f32_dpp v98, v63, v79 row_ror:15 row_mask:0xf bank_mask:0xf bound_ctrl:1
	v_mul_f32_e32 v62, v98, v99
	v_mul_f32_e32 v59, v62, v59
	v_cndmask_b32_e64 v62, v56, v64, s[42:43]
	v_cndmask_b32_e64 v64, v52, v42, s[40:41]
	v_fma_f32 v98, v52, v84, v96
	v_fmac_f32_dpp v98, v60, v72 row_ror:1 row_mask:0xf bank_mask:0xf bound_ctrl:1
	v_cndmask_b32_e64 v63, v56, v46, s[40:41]
	v_fmac_f32_dpp v98, v64, v88 row_ror:15 row_mask:0xf bank_mask:0xf bound_ctrl:1
	v_mul_f32_e32 v60, 0xbfb8aa3b, v98
	v_exp_f32_e32 v60, v60
	v_fma_f32 v64, v56, v76, v92
	v_fmac_f32_dpp v64, v62, v68 row_ror:1 row_mask:0xf bank_mask:0xf bound_ctrl:1
	v_add_f32_e32 v60, 1.0, v60
	v_rcp_f32_e32 v60, v60
	v_fmac_f32_dpp v64, v63, v80 row_ror:15 row_mask:0xf bank_mask:0xf bound_ctrl:1
	v_mul_f32_e32 v62, v64, v98
	v_cndmask_b32_e64 v61, v53, v61, s[42:43]
	v_mul_f32_e32 v60, v62, v60
	v_cndmask_b32_e64 v62, v57, v65, s[42:43]
	v_cndmask_b32_e64 v64, v53, v43, s[40:41]
	v_fma_f32 v65, v53, v85, v97
	v_fmac_f32_dpp v65, v61, v73 row_ror:1 row_mask:0xf bank_mask:0xf bound_ctrl:1
	v_cndmask_b32_e64 v63, v57, v47, s[40:41]
	v_fmac_f32_dpp v65, v64, v89 row_ror:15 row_mask:0xf bank_mask:0xf bound_ctrl:1
	v_mul_f32_e32 v61, 0xbfb8aa3b, v65
	v_exp_f32_e32 v61, v61
	v_fma_f32 v64, v57, v77, v93
	v_fmac_f32_dpp v64, v62, v69 row_ror:1 row_mask:0xf bank_mask:0xf bound_ctrl:1
	v_add_f32_e32 v61, 1.0, v61
	v_rcp_f32_e32 v61, v61
	v_fmac_f32_dpp v64, v63, v81 row_ror:15 row_mask:0xf bank_mask:0xf bound_ctrl:1
	v_mul_f32_e32 v62, v64, v65
	v_mul_f32_e32 v61, v62, v61
	v_cvt_pk_bf16_f32 v58, v58, v59
	v_cvt_pk_bf16_f32 v59, v60, v61
	s_nop 0
	v_mov_b32_e32 v116, v206
	v_mov_b32_e32 v117, v207
	v_mov_b32_e32 v118, v58
	v_mov_b32_e32 v119, v59
	s_and_saveexec_b64 s[2:3], s[46:47]
	s_cbranch_execz .LBB0_454
	v_mov_b64_e32 v[60:61], s[20:21]
	s_movk_i32 s6, 0x1800
	v_mad_i64_i32 v[60:61], s[6:7], v48, s6, v[60:61]
	v_lshl_add_u64 v[60:61], v[188:189], 1, v[60:61]
	global_store_dwordx4 v[60:61], v[116:119], off
;     __device__ __forceinline__ void operator()(const f32x4 (&acc)[2][2][4][2], const pg8::Unit& u, int wr, int wc, int fr, int fq) const {
;     ...
;             for (int n = 0; n < 2; ++n) {
;                 f32x4 wv[3], wg[3], bv, bg;
; #pragma unroll
;                 for (int k = 0; k < 3; ++k) { wv[k] = *(const f32x4*)(cw + k * 6144 + cv + 4 * n); wg[k] = *(const f32x4*)(cw + k * 6144 + DFF + cv + 4 * n); }
;                 bv = *(const f32x4*)(cbias + cv + 4 * n); bg = *(const f32x4*)(cbias + DFF + cv + 4 * n);
; #pragma unroll
;                 for (int ai = 0; ai < 2; ++ai) { const int s = 2 * ai + wr;
; #pragma unroll
;                     for (int m = 0; m < 4; ++m) {
;                         const int rl = 128 * ai + 64 * wr + 16 * m + fr, row = R0 + rl;
;                         f32x4 xpv, xpg, xnv, xng;
;                         if (m == 0) { const LAS float* p = xb + ((s > 0 ? s - 1 : 0) * 2 + 1) * 256 + cl + 4 * n; xpv = *(const LAS f32x4*)p; xpg = *(const LAS f32x4*)(p + 128); }
;                         if (m == 3) { const LAS float* p = xb + ((s < 3 ? s + 1 : 3) * 2 + 0) * 256 + cl + 4 * n; xnv = *(const LAS f32x4*)p; xng = *(const LAS f32x4*)(p + 128); }
;                         float o[4];
; #pragma unroll
;                         for (int e = 0; e < 4; ++e) {
;                             const float cvv = acc[ai][0][m][n][e], cgg = acc[ai][1][m][n][e];
;                             const float upv = m > 0 ? acc[ai][0][m > 0 ? m - 1 : 0][n][e] : xpv[e], upg = m > 0 ? acc[ai][1][m > 0 ? m - 1 : 0][n][e] : xpg[e];
;                             const float dnv = m < 3 ? acc[ai][0][m < 3 ? m + 1 : 3][n][e] : xnv[e], dng = m < 3 ? acc[ai][1][m < 3 ? m + 1 : 3][n][e] : xng[e];
;                             const float xpv_ = fr == 15 ? upv : cvv, xpg_ = fr == 15 ? upg : cgg;
;                             const float xnv_ = fr == 0 ? dnv : cvv, xng_ = fr == 0 ? dng : cgg;
;                             float val = bv[e] + wv[1][e] * cvv; val += wv[0][e] * dppf<0x121>(xpv_); val += wv[2][e] * dppf<0x12F>(xnv_);
;                             float gt = bg[e] + wg[1][e] * cgg; gt += wg[0][e] * dppf<0x121>(xpg_); gt += wg[2][e] * dppf<0x12F>(xng_);
;                             o[e] = val * gt * sigmoidf_(gt);
;                         }
;                         u32x2 ow; ow.x = pg8::cvt_pk_bf16(o[0], o[1]); ow.y = pg8::cvt_pk_bf16(o[2], o[3]);
.LBB0_454:
	s_or_b64 exec, exec, s[2:3]
	v_cndmask_b32_e64 v50, v40, v50, s[42:43]
	v_cndmask_b32_e64 v58, v40, v32, s[40:41]
	v_fma_f32 v59, v40, v82, v94
	v_fmac_f32_dpp v59, v50, v70 row_ror:1 row_mask:0xf bank_mask:0xf bound_ctrl:1
	v_cndmask_b32_e64 v48, v44, v54, s[42:43]
	v_fmac_f32_dpp v59, v58, v86 row_ror:15 row_mask:0xf bank_mask:0xf bound_ctrl:1
	v_mul_f32_e32 v50, 0xbfb8aa3b, v59
	v_exp_f32_e32 v50, v50
	v_fma_f32 v58, v44, v74, v90
	v_fmac_f32_dpp v58, v48, v66 row_ror:1 row_mask:0xf bank_mask:0xf bound_ctrl:1
	v_add_f32_e32 v48, 1.0, v50
	v_cndmask_b32_e64 v54, v44, v36, s[40:41]
	v_rcp_f32_e32 v48, v48
	v_cndmask_b32_e64 v51, v41, v51, s[42:43]
	v_fmac_f32_dpp v58, v54, v78 row_ror:15 row_mask:0xf bank_mask:0xf bound_ctrl:1
	v_mul_f32_e32 v50, v58, v59
	v_mul_f32_e32 v48, v50, v48
	v_cndmask_b32_e64 v50, v45, v55, s[42:43]
	v_cndmask_b32_e64 v55, v41, v33, s[40:41]
	v_fma_f32 v58, v41, v83, v95
	v_fmac_f32_dpp v58, v51, v71 row_ror:1 row_mask:0xf bank_mask:0xf bound_ctrl:1
	v_fmac_f32_dpp v58, v55, v87 row_ror:15 row_mask:0xf bank_mask:0xf bound_ctrl:1
	v_mul_f32_e32 v51, 0xbfb8aa3b, v58
	v_exp_f32_e32 v51, v51
	v_fma_f32 v55, v45, v75, v91
	v_fmac_f32_dpp v55, v50, v67 row_ror:1 row_mask:0xf bank_mask:0xf bound_ctrl:1
	v_cndmask_b32_e64 v54, v45, v37, s[40:41]
	v_add_f32_e32 v50, 1.0, v51
	v_rcp_f32_e32 v50, v50
	v_fmac_f32_dpp v55, v54, v79 row_ror:15 row_mask:0xf bank_mask:0xf bound_ctrl:1
	v_mul_f32_e32 v51, v55, v58
	v_cndmask_b32_e64 v52, v42, v52, s[42:43]
	v_mul_f32_e32 v50, v51, v50
	v_cndmask_b32_e64 v51, v46, v56, s[42:43]
	v_cndmask_b32_e64 v55, v42, v34, s[40:41]
	v_fma_f32 v56, v42, v84, v96
	v_fmac_f32_dpp v56, v52, v72 row_ror:1 row_mask:0xf bank_mask:0xf bound_ctrl:1
	v_cndmask_b32_e64 v54, v46, v38, s[40:41]
	v_fmac_f32_dpp v56, v55, v88 row_ror:15 row_mask:0xf bank_mask:0xf bound_ctrl:1
	v_mul_f32_e32 v52, 0xbfb8aa3b, v56
	v_exp_f32_e32 v52, v52
	v_fma_f32 v55, v46, v76, v92
	v_fmac_f32_dpp v55, v51, v68 row_ror:1 row_mask:0xf bank_mask:0xf bound_ctrl:1
	v_add_f32_e32 v51, 1.0, v52
	v_fmac_f32_dpp v55, v54, v80 row_ror:15 row_mask:0xf bank_mask:0xf bound_ctrl:1
	v_cndmask_b32_e64 v53, v43, v53, s[42:43]
	v_mul_f32_e32 v52, v55, v56
	v_cndmask_b32_e64 v55, v43, v35, s[40:41]
	v_fma_f32 v56, v43, v85, v97
	v_fmac_f32_dpp v56, v53, v73 row_ror:1 row_mask:0xf bank_mask:0xf bound_ctrl:1
	v_rcp_f32_e32 v51, v51
	v_fmac_f32_dpp v56, v55, v89 row_ror:15 row_mask:0xf bank_mask:0xf bound_ctrl:1
	v_mul_f32_e32 v53, 0xbfb8aa3b, v56
	v_exp_f32_e32 v53, v53
	v_mul_f32_e32 v51, v52, v51
	v_cndmask_b32_e64 v52, v47, v57, s[42:43]
	v_fma_f32 v55, v47, v77, v93
	v_cndmask_b32_e64 v54, v47, v39, s[40:41]
	v_fmac_f32_dpp v55, v52, v69 row_ror:1 row_mask:0xf bank_mask:0xf bound_ctrl:1
	v_add_f32_e32 v52, 1.0, v53
	v_rcp_f32_e32 v52, v52
	v_fmac_f32_dpp v55, v54, v81 row_ror:15 row_mask:0xf bank_mask:0xf bound_ctrl:1
	v_mul_f32_e32 v53, v55, v56
	v_mul_f32_e32 v52, v53, v52
	v_cvt_pk_bf16_f32 v50, v48, v50
	v_cvt_pk_bf16_f32 v51, v51, v52
	s_nop 0
	v_mov_b32_e32 v116, v208
	v_mov_b32_e32 v117, v209
	v_mov_b32_e32 v118, v50
	v_mov_b32_e32 v119, v51
	s_and_saveexec_b64 s[2:3], s[48:49]
	s_cbranch_execz .LBB0_456
	v_mov_b64_e32 v[52:53], s[20:21]
	s_movk_i32 s6, 0x1800
	v_mad_i64_i32 v[52:53], s[6:7], v122, s6, v[52:53]
	v_lshl_add_u64 v[52:53], v[188:189], 1, v[52:53]
	global_store_dwordx4 v[52:53], v[116:119], off
.LBB0_456:
	s_or_b64 exec, exec, s[2:3]
	ds_read_b128 v[50:53], v235 offset:2064
	ds_read_b128 v[54:57], v235 offset:2576
	v_cndmask_b32_e64 v40, v32, v40, s[42:43]
	v_cndmask_b32_e64 v44, v36, v44, s[42:43]
	s_waitcnt lgkmcnt(1)
	v_cndmask_b32_e64 v48, v36, v50, s[40:41]
	s_waitcnt lgkmcnt(0)
	v_cndmask_b32_e64 v50, v32, v54, s[40:41]
	v_fma_f32 v32, v32, v82, v94
	v_fmac_f32_dpp v32, v40, v70 row_ror:1 row_mask:0xf bank_mask:0xf bound_ctrl:1
	v_fma_f32 v36, v36, v74, v90
	v_fmac_f32_dpp v32, v50, v86 row_ror:15 row_mask:0xf bank_mask:0xf bound_ctrl:1
	v_mul_f32_e32 v40, 0xbfb8aa3b, v32
	v_exp_f32_e32 v40, v40
	v_fmac_f32_dpp v36, v44, v66 row_ror:1 row_mask:0xf bank_mask:0xf bound_ctrl:1
	v_add_f32_e32 v40, 1.0, v40
	v_rcp_f32_e32 v40, v40
	v_fmac_f32_dpp v36, v48, v78 row_ror:15 row_mask:0xf bank_mask:0xf bound_ctrl:1
	v_mul_f32_e32 v32, v36, v32
	v_mul_f32_e32 v32, v32, v40
	v_cndmask_b32_e64 v40, v33, v41, s[42:43]
	v_cndmask_b32_e64 v44, v33, v55, s[40:41]
	v_fma_f32 v33, v33, v83, v95
	v_fmac_f32_dpp v33, v40, v71 row_ror:1 row_mask:0xf bank_mask:0xf bound_ctrl:1
	v_cndmask_b32_e64 v36, v37, v45, s[42:43]
	v_fmac_f32_dpp v33, v44, v87 row_ror:15 row_mask:0xf bank_mask:0xf bound_ctrl:1
	v_mul_f32_e32 v40, 0xbfb8aa3b, v33
	v_exp_f32_e32 v40, v40
	v_cndmask_b32_e64 v41, v37, v51, s[40:41]
	v_fma_f32 v37, v37, v75, v91
	v_fmac_f32_dpp v37, v36, v67 row_ror:1 row_mask:0xf bank_mask:0xf bound_ctrl:1
	v_add_f32_e32 v36, 1.0, v40
	v_fmac_f32_dpp v37, v41, v79 row_ror:15 row_mask:0xf bank_mask:0xf bound_ctrl:1
	v_mul_f32_e32 v33, v37, v33
	v_cndmask_b32_e64 v37, v34, v42, s[42:43]
	v_cndmask_b32_e64 v41, v34, v56, s[40:41]
	v_fma_f32 v34, v34, v84, v96
	v_fmac_f32_dpp v34, v37, v72 row_ror:1 row_mask:0xf bank_mask:0xf bound_ctrl:1
	v_rcp_f32_e32 v36, v36
	v_fmac_f32_dpp v34, v41, v88 row_ror:15 row_mask:0xf bank_mask:0xf bound_ctrl:1
	v_mul_f32_e32 v37, 0xbfb8aa3b, v34
	v_exp_f32_e32 v37, v37
	v_mul_f32_e32 v33, v33, v36
	v_cndmask_b32_e64 v36, v38, v46, s[42:43]
	v_cndmask_b32_e64 v40, v38, v52, s[40:41]
	v_fma_f32 v38, v38, v76, v92
	v_fmac_f32_dpp v38, v36, v68 row_ror:1 row_mask:0xf bank_mask:0xf bound_ctrl:1
	v_add_f32_e32 v36, 1.0, v37
	v_fmac_f32_dpp v38, v40, v80 row_ror:15 row_mask:0xf bank_mask:0xf bound_ctrl:1
	v_cndmask_b32_e64 v37, v35, v43, s[42:43]
	v_cndmask_b32_e64 v40, v35, v57, s[40:41]
	v_fma_f32 v35, v35, v85, v97
	v_fmac_f32_dpp v35, v37, v73 row_ror:1 row_mask:0xf bank_mask:0xf bound_ctrl:1
	v_rcp_f32_e32 v36, v36
	v_fmac_f32_dpp v35, v40, v89 row_ror:15 row_mask:0xf bank_mask:0xf bound_ctrl:1
	v_mul_f32_e32 v37, 0xbfb8aa3b, v35
	v_exp_f32_e32 v37, v37
	v_mul_f32_e32 v34, v38, v34
	v_mul_f32_e32 v34, v34, v36
	v_cndmask_b32_e64 v36, v39, v47, s[42:43]
	v_cndmask_b32_e64 v38, v39, v53, s[40:41]
	v_fma_f32 v39, v39, v77, v93
	v_fmac_f32_dpp v39, v36, v69 row_ror:1 row_mask:0xf bank_mask:0xf bound_ctrl:1
	v_add_f32_e32 v36, 1.0, v37
	v_rcp_f32_e32 v36, v36
	v_fmac_f32_dpp v39, v38, v81 row_ror:15 row_mask:0xf bank_mask:0xf bound_ctrl:1
	v_mul_f32_e32 v35, v39, v35
	v_mul_f32_e32 v35, v35, v36
	v_cvt_pk_bf16_f32 v32, v32, v33
	v_cvt_pk_bf16_f32 v33, v34, v35
	s_nop 0
	v_mov_b32_e32 v116, v210
	v_mov_b32_e32 v117, v211
	v_mov_b32_e32 v118, v32
	v_mov_b32_e32 v119, v33
	s_and_saveexec_b64 s[2:3], s[50:51]
	s_cbranch_execz .LBB0_458
	v_mov_b64_e32 v[34:35], s[20:21]
	s_movk_i32 s6, 0x1800
	v_mad_i64_i32 v[34:35], s[6:7], v114, s6, v[34:35]
	v_lshl_add_u64 v[34:35], v[188:189], 1, v[34:35]
	global_store_dwordx4 v[34:35], v[116:119], off
;     __device__ __forceinline__ void operator()(const f32x4 (&acc)[2][2][4][2], const pg8::Unit& u, int wr, int wc, int fr, int fq) const {
;     ...
;             for (int n = 0; n < 2; ++n) {
;                 f32x4 wv[3], wg[3], bv, bg;
; #pragma unroll
;                 for (int k = 0; k < 3; ++k) { wv[k] = *(const f32x4*)(cw + k * 6144 + cv + 4 * n); wg[k] = *(const f32x4*)(cw + k * 6144 + DFF + cv + 4 * n); }
;                 bv = *(const f32x4*)(cbias + cv + 4 * n); bg = *(const f32x4*)(cbias + DFF + cv + 4 * n);
; #pragma unroll
;                 for (int ai = 0; ai < 2; ++ai) { const int s = 2 * ai + wr;
; #pragma unroll
;                     for (int m = 0; m < 4; ++m) {
;                         const int rl = 128 * ai + 64 * wr + 16 * m + fr, row = R0 + rl;
;                         f32x4 xpv, xpg, xnv, xng;
;                         if (m == 0) { const LAS float* p = xb + ((s > 0 ? s - 1 : 0) * 2 + 1) * 256 + cl + 4 * n; xpv = *(const LAS f32x4*)p; xpg = *(const LAS f32x4*)(p + 128); }
;                         if (m == 3) { const LAS float* p = xb + ((s < 3 ? s + 1 : 3) * 2 + 0) * 256 + cl + 4 * n; xnv = *(const LAS f32x4*)p; xng = *(const LAS f32x4*)(p + 128); }
;                         float o[4];
; #pragma unroll
;                         for (int e = 0; e < 4; ++e) {
;                             const float cvv = acc[ai][0][m][n][e], cgg = acc[ai][1][m][n][e];
;                             const float upv = m > 0 ? acc[ai][0][m > 0 ? m - 1 : 0][n][e] : xpv[e], upg = m > 0 ? acc[ai][1][m > 0 ? m - 1 : 0][n][e] : xpg[e];
;                             const float dnv = m < 3 ? acc[ai][0][m < 3 ? m + 1 : 3][n][e] : xnv[e], dng = m < 3 ? acc[ai][1][m < 3 ? m + 1 : 3][n][e] : xng[e];
;                             const float xpv_ = fr == 15 ? upv : cvv, xpg_ = fr == 15 ? upg : cgg;
;                             const float xnv_ = fr == 0 ? dnv : cvv, xng_ = fr == 0 ? dng : cgg;
;                             float val = bv[e] + wv[1][e] * cvv; val += wv[0][e] * dppf<0x121>(xpv_); val += wv[2][e] * dppf<0x12F>(xnv_);
;                             float gt = bg[e] + wg[1][e] * cgg; gt += wg[0][e] * dppf<0x121>(xpg_); gt += wg[2][e] * dppf<0x12F>(xng_);
;                             o[e] = val * gt * sigmoidf_(gt);
;                         }
;                         u32x2 ow; ow.x = pg8::cvt_pk_bf16(o[0], o[1]); ow.y = pg8::cvt_pk_bf16(o[2], o[3]);
.LBB0_458:
	s_or_b64 exec, exec, s[2:3]
	ds_read_b128 v[32:35], v240
	ds_read_b128 v[36:39], v241
	v_cndmask_b32_e64 v41, v24, v16, s[40:41]
	v_fma_f32 v42, v24, v82, v94
	v_cndmask_b32_e64 v40, v28, v20, s[40:41]
	s_waitcnt lgkmcnt(1)
	v_cndmask_b32_e64 v32, v28, v32, s[42:43]
	s_waitcnt lgkmcnt(0)
	v_cndmask_b32_e64 v36, v24, v36, s[42:43]
	v_cndmask_b32_e64 v33, v29, v33, s[42:43]
	s_nop 0
	v_fmac_f32_dpp v42, v36, v70 row_ror:1 row_mask:0xf bank_mask:0xf bound_ctrl:1
	v_fmac_f32_dpp v42, v41, v86 row_ror:15 row_mask:0xf bank_mask:0xf bound_ctrl:1
	v_mul_f32_e32 v36, 0xbfb8aa3b, v42
	v_exp_f32_e32 v36, v36
	v_fma_f32 v41, v28, v74, v90
	v_fmac_f32_dpp v41, v32, v66 row_ror:1 row_mask:0xf bank_mask:0xf bound_ctrl:1
	v_cndmask_b32_e64 v34, v30, v34, s[42:43]
	v_add_f32_e32 v32, 1.0, v36
	v_rcp_f32_e32 v32, v32
	v_fmac_f32_dpp v41, v40, v78 row_ror:15 row_mask:0xf bank_mask:0xf bound_ctrl:1
	v_mul_f32_e32 v36, v41, v42
	v_mul_f32_e32 v32, v36, v32
	v_cndmask_b32_e64 v36, v25, v37, s[42:43]
	v_cndmask_b32_e64 v40, v25, v17, s[40:41]
	v_fma_f32 v41, v25, v83, v95
	v_fmac_f32_dpp v41, v36, v71 row_ror:1 row_mask:0xf bank_mask:0xf bound_ctrl:1
	v_cndmask_b32_e64 v37, v29, v21, s[40:41]
	v_fmac_f32_dpp v41, v40, v87 row_ror:15 row_mask:0xf bank_mask:0xf bound_ctrl:1
	v_mul_f32_e32 v36, 0xbfb8aa3b, v41
	v_exp_f32_e32 v36, v36
	v_fma_f32 v40, v29, v75, v91
	v_fmac_f32_dpp v40, v33, v67 row_ror:1 row_mask:0xf bank_mask:0xf bound_ctrl:1
	v_add_f32_e32 v33, 1.0, v36
	v_rcp_f32_e32 v33, v33
	v_fmac_f32_dpp v40, v37, v79 row_ror:15 row_mask:0xf bank_mask:0xf bound_ctrl:1
	v_mul_f32_e32 v36, v40, v41
	v_mul_f32_e32 v33, v36, v33
	v_cndmask_b32_e64 v36, v26, v38, s[42:43]
	v_cndmask_b32_e64 v38, v26, v18, s[40:41]
	v_fma_f32 v40, v26, v84, v96
	v_fmac_f32_dpp v40, v36, v72 row_ror:1 row_mask:0xf bank_mask:0xf bound_ctrl:1
	v_cndmask_b32_e64 v37, v30, v22, s[40:41]
	v_fmac_f32_dpp v40, v38, v88 row_ror:15 row_mask:0xf bank_mask:0xf bound_ctrl:1
	v_mul_f32_e32 v36, 0xbfb8aa3b, v40
	v_exp_f32_e32 v36, v36
	v_fma_f32 v38, v30, v76, v92
	v_fmac_f32_dpp v38, v34, v68 row_ror:1 row_mask:0xf bank_mask:0xf bound_ctrl:1
	v_cndmask_b32_e64 v35, v31, v35, s[42:43]
	v_add_f32_e32 v34, 1.0, v36
	v_rcp_f32_e32 v34, v34
	v_fmac_f32_dpp v38, v37, v80 row_ror:15 row_mask:0xf bank_mask:0xf bound_ctrl:1
	v_mul_f32_e32 v36, v38, v40
	v_mul_f32_e32 v34, v36, v34
	v_cndmask_b32_e64 v36, v27, v39, s[42:43]
	v_cndmask_b32_e64 v38, v27, v19, s[40:41]
	v_fma_f32 v39, v27, v85, v97
	v_fmac_f32_dpp v39, v36, v73 row_ror:1 row_mask:0xf bank_mask:0xf bound_ctrl:1
	v_fmac_f32_dpp v39, v38, v89 row_ror:15 row_mask:0xf bank_mask:0xf bound_ctrl:1
	v_mul_f32_e32 v36, 0xbfb8aa3b, v39
	v_exp_f32_e32 v36, v36
	v_fma_f32 v38, v31, v77, v93
	v_fmac_f32_dpp v38, v35, v69 row_ror:1 row_mask:0xf bank_mask:0xf bound_ctrl:1
	v_cndmask_b32_e64 v37, v31, v23, s[40:41]
	v_add_f32_e32 v35, 1.0, v36
	v_rcp_f32_e32 v35, v35
	v_fmac_f32_dpp v38, v37, v81 row_ror:15 row_mask:0xf bank_mask:0xf bound_ctrl:1
	v_mul_f32_e32 v36, v38, v39
	v_mul_f32_e32 v35, v36, v35
	v_cvt_pk_bf16_f32 v32, v32, v33
	v_cvt_pk_bf16_f32 v33, v34, v35
	s_nop 0
	v_mov_b32_e32 v116, v212
	v_mov_b32_e32 v117, v213
	v_mov_b32_e32 v118, v32
	v_mov_b32_e32 v119, v33
	s_and_saveexec_b64 s[2:3], s[52:53]
	s_cbranch_execz .LBB0_460
	v_mov_b64_e32 v[34:35], s[20:21]
	s_movk_i32 s6, 0x1800
	v_mad_i64_i32 v[34:35], s[6:7], v106, s6, v[34:35]
	v_lshl_add_u64 v[34:35], v[188:189], 1, v[34:35]
	global_store_dwordx4 v[34:35], v[116:119], off
.LBB0_460:
	s_or_b64 exec, exec, s[2:3]
	v_cndmask_b32_e64 v24, v16, v24, s[42:43]
	v_cndmask_b32_e64 v33, v16, v8, s[40:41]
	v_fma_f32 v34, v16, v82, v94
	v_cndmask_b32_e64 v28, v20, v28, s[42:43]
	v_fmac_f32_dpp v34, v24, v70 row_ror:1 row_mask:0xf bank_mask:0xf bound_ctrl:1
	v_cndmask_b32_e64 v32, v20, v12, s[40:41]
	v_fmac_f32_dpp v34, v33, v86 row_ror:15 row_mask:0xf bank_mask:0xf bound_ctrl:1
	v_fma_f32 v33, v20, v74, v90
	v_mul_f32_e32 v24, 0xbfb8aa3b, v34
	v_fmac_f32_dpp v33, v28, v66 row_ror:1 row_mask:0xf bank_mask:0xf bound_ctrl:1
	v_exp_f32_e32 v24, v24
	v_fmac_f32_dpp v33, v32, v78 row_ror:15 row_mask:0xf bank_mask:0xf bound_ctrl:1
	v_cndmask_b32_e64 v25, v17, v25, s[42:43]
	v_mul_f32_e32 v28, v33, v34
	v_cndmask_b32_e64 v32, v17, v9, s[40:41]
	v_fma_f32 v33, v17, v83, v95
	v_fmac_f32_dpp v33, v25, v71 row_ror:1 row_mask:0xf bank_mask:0xf bound_ctrl:1
	v_add_f32_e32 v24, 1.0, v24
	v_fmac_f32_dpp v33, v32, v87 row_ror:15 row_mask:0xf bank_mask:0xf bound_ctrl:1
	v_mul_f32_e32 v25, 0xbfb8aa3b, v33
	v_rcp_f32_e32 v24, v24
	v_exp_f32_e32 v25, v25
	v_fma_f32 v32, v21, v75, v91
	v_cndmask_b32_e64 v26, v18, v26, s[42:43]
	v_mul_f32_e32 v24, v28, v24
	v_cndmask_b32_e64 v28, v21, v29, s[42:43]
	v_add_f32_e32 v25, 1.0, v25
	v_cndmask_b32_e64 v29, v21, v13, s[40:41]
	v_rcp_f32_e32 v25, v25
	v_fmac_f32_dpp v32, v28, v67 row_ror:1 row_mask:0xf bank_mask:0xf bound_ctrl:1
	v_fmac_f32_dpp v32, v29, v79 row_ror:15 row_mask:0xf bank_mask:0xf bound_ctrl:1
	v_mul_f32_e32 v28, v32, v33
	v_mul_f32_e32 v25, v28, v25
	v_cndmask_b32_e64 v28, v22, v30, s[42:43]
	v_cndmask_b32_e64 v30, v18, v10, s[40:41]
	v_fma_f32 v32, v18, v84, v96
	v_fmac_f32_dpp v32, v26, v72 row_ror:1 row_mask:0xf bank_mask:0xf bound_ctrl:1
	v_cndmask_b32_e64 v29, v22, v14, s[40:41]
	v_fmac_f32_dpp v32, v30, v88 row_ror:15 row_mask:0xf bank_mask:0xf bound_ctrl:1
	v_mul_f32_e32 v26, 0xbfb8aa3b, v32
	v_exp_f32_e32 v26, v26
	v_fma_f32 v30, v22, v76, v92
	v_fmac_f32_dpp v30, v28, v68 row_ror:1 row_mask:0xf bank_mask:0xf bound_ctrl:1
	v_add_f32_e32 v26, 1.0, v26
	v_rcp_f32_e32 v26, v26
	v_fmac_f32_dpp v30, v29, v80 row_ror:15 row_mask:0xf bank_mask:0xf bound_ctrl:1
	v_mul_f32_e32 v28, v30, v32
	v_cndmask_b32_e64 v27, v19, v27, s[42:43]
	v_mul_f32_e32 v26, v28, v26
	v_cndmask_b32_e64 v28, v23, v31, s[42:43]
	v_cndmask_b32_e64 v30, v19, v11, s[40:41]
	v_fma_f32 v31, v19, v85, v97
	v_fmac_f32_dpp v31, v27, v73 row_ror:1 row_mask:0xf bank_mask:0xf bound_ctrl:1
	v_cndmask_b32_e64 v29, v23, v15, s[40:41]
	v_fmac_f32_dpp v31, v30, v89 row_ror:15 row_mask:0xf bank_mask:0xf bound_ctrl:1
	v_mul_f32_e32 v27, 0xbfb8aa3b, v31
	v_exp_f32_e32 v27, v27
	v_fma_f32 v30, v23, v77, v93
	v_fmac_f32_dpp v30, v28, v69 row_ror:1 row_mask:0xf bank_mask:0xf bound_ctrl:1
	v_add_f32_e32 v27, 1.0, v27
	v_rcp_f32_e32 v27, v27
	v_fmac_f32_dpp v30, v29, v81 row_ror:15 row_mask:0xf bank_mask:0xf bound_ctrl:1
	v_mul_f32_e32 v28, v30, v31
	v_mul_f32_e32 v27, v28, v27
	v_cvt_pk_bf16_f32 v24, v24, v25
	v_cvt_pk_bf16_f32 v25, v26, v27
	s_nop 0
	v_mov_b32_e32 v116, v214
	v_mov_b32_e32 v117, v215
	v_mov_b32_e32 v118, v24
	v_mov_b32_e32 v119, v25
	s_and_saveexec_b64 s[2:3], s[54:55]
	s_cbranch_execz .LBB0_462
	v_mov_b64_e32 v[26:27], s[20:21]
	s_movk_i32 s6, 0x1800
	v_mad_i64_i32 v[26:27], s[6:7], v108, s6, v[26:27]
	v_lshl_add_u64 v[26:27], v[188:189], 1, v[26:27]
	global_store_dwordx4 v[26:27], v[116:119], off
;     __device__ __forceinline__ void operator()(const f32x4 (&acc)[2][2][4][2], const pg8::Unit& u, int wr, int wc, int fr, int fq) const {
;     ...
;             for (int n = 0; n < 2; ++n) {
;                 f32x4 wv[3], wg[3], bv, bg;
; #pragma unroll
;                 for (int k = 0; k < 3; ++k) { wv[k] = *(const f32x4*)(cw + k * 6144 + cv + 4 * n); wg[k] = *(const f32x4*)(cw + k * 6144 + DFF + cv + 4 * n); }
;                 bv = *(const f32x4*)(cbias + cv + 4 * n); bg = *(const f32x4*)(cbias + DFF + cv + 4 * n);
; #pragma unroll
;                 for (int ai = 0; ai < 2; ++ai) { const int s = 2 * ai + wr;
; #pragma unroll
;                     for (int m = 0; m < 4; ++m) {
;                         const int rl = 128 * ai + 64 * wr + 16 * m + fr, row = R0 + rl;
;                         f32x4 xpv, xpg, xnv, xng;
;                         if (m == 0) { const LAS float* p = xb + ((s > 0 ? s - 1 : 0) * 2 + 1) * 256 + cl + 4 * n; xpv = *(const LAS f32x4*)p; xpg = *(const LAS f32x4*)(p + 128); }
;                         if (m == 3) { const LAS float* p = xb + ((s < 3 ? s + 1 : 3) * 2 + 0) * 256 + cl + 4 * n; xnv = *(const LAS f32x4*)p; xng = *(const LAS f32x4*)(p + 128); }
;                         float o[4];
; #pragma unroll
;                         for (int e = 0; e < 4; ++e) {
;                             const float cvv = acc[ai][0][m][n][e], cgg = acc[ai][1][m][n][e];
;                             const float upv = m > 0 ? acc[ai][0][m > 0 ? m - 1 : 0][n][e] : xpv[e], upg = m > 0 ? acc[ai][1][m > 0 ? m - 1 : 0][n][e] : xpg[e];
;                             const float dnv = m < 3 ? acc[ai][0][m < 3 ? m + 1 : 3][n][e] : xnv[e], dng = m < 3 ? acc[ai][1][m < 3 ? m + 1 : 3][n][e] : xng[e];
;                             const float xpv_ = fr == 15 ? upv : cvv, xpg_ = fr == 15 ? upg : cgg;
;                             const float xnv_ = fr == 0 ? dnv : cvv, xng_ = fr == 0 ? dng : cgg;
;                             float val = bv[e] + wv[1][e] * cvv; val += wv[0][e] * dppf<0x121>(xpv_); val += wv[2][e] * dppf<0x12F>(xnv_);
;                             float gt = bg[e] + wg[1][e] * cgg; gt += wg[0][e] * dppf<0x121>(xpg_); gt += wg[2][e] * dppf<0x12F>(xng_);
;                             o[e] = val * gt * sigmoidf_(gt);
;                         }
;                         u32x2 ow; ow.x = pg8::cvt_pk_bf16(o[0], o[1]); ow.y = pg8::cvt_pk_bf16(o[2], o[3]);
.LBB0_462:
	s_or_b64 exec, exec, s[2:3]
	v_cndmask_b32_e64 v16, v8, v16, s[42:43]
	v_cndmask_b32_e64 v25, v8, v0, s[40:41]
	v_fma_f32 v26, v8, v82, v94
	v_cndmask_b32_e64 v20, v12, v20, s[42:43]
	v_fmac_f32_dpp v26, v16, v70 row_ror:1 row_mask:0xf bank_mask:0xf bound_ctrl:1
	v_cndmask_b32_e64 v24, v12, v4, s[40:41]
	v_fmac_f32_dpp v26, v25, v86 row_ror:15 row_mask:0xf bank_mask:0xf bound_ctrl:1
	v_fma_f32 v25, v12, v74, v90
	v_mul_f32_e32 v16, 0xbfb8aa3b, v26
	v_fmac_f32_dpp v25, v20, v66 row_ror:1 row_mask:0xf bank_mask:0xf bound_ctrl:1
	v_exp_f32_e32 v16, v16
	v_fmac_f32_dpp v25, v24, v78 row_ror:15 row_mask:0xf bank_mask:0xf bound_ctrl:1
	v_cndmask_b32_e64 v17, v9, v17, s[42:43]
	v_mul_f32_e32 v20, v25, v26
	v_cndmask_b32_e64 v24, v9, v1, s[40:41]
	v_fma_f32 v25, v9, v83, v95
	v_fmac_f32_dpp v25, v17, v71 row_ror:1 row_mask:0xf bank_mask:0xf bound_ctrl:1
	v_add_f32_e32 v16, 1.0, v16
	v_fmac_f32_dpp v25, v24, v87 row_ror:15 row_mask:0xf bank_mask:0xf bound_ctrl:1
	v_mul_f32_e32 v17, 0xbfb8aa3b, v25
	v_rcp_f32_e32 v16, v16
	v_exp_f32_e32 v17, v17
	v_fma_f32 v24, v13, v75, v91
	v_cndmask_b32_e64 v18, v10, v18, s[42:43]
	v_mul_f32_e32 v16, v20, v16
	v_cndmask_b32_e64 v20, v13, v21, s[42:43]
	v_add_f32_e32 v17, 1.0, v17
	v_cndmask_b32_e64 v21, v13, v5, s[40:41]
	v_rcp_f32_e32 v17, v17
	v_fmac_f32_dpp v24, v20, v67 row_ror:1 row_mask:0xf bank_mask:0xf bound_ctrl:1
	v_fmac_f32_dpp v24, v21, v79 row_ror:15 row_mask:0xf bank_mask:0xf bound_ctrl:1
	v_mul_f32_e32 v20, v24, v25
	v_mul_f32_e32 v17, v20, v17
	v_cndmask_b32_e64 v20, v14, v22, s[42:43]
	v_cndmask_b32_e64 v22, v10, v2, s[40:41]
	v_fma_f32 v24, v10, v84, v96
	v_fmac_f32_dpp v24, v18, v72 row_ror:1 row_mask:0xf bank_mask:0xf bound_ctrl:1
	v_cndmask_b32_e64 v21, v14, v6, s[40:41]
	v_fmac_f32_dpp v24, v22, v88 row_ror:15 row_mask:0xf bank_mask:0xf bound_ctrl:1
	v_mul_f32_e32 v18, 0xbfb8aa3b, v24
	v_exp_f32_e32 v18, v18
	v_fma_f32 v22, v14, v76, v92
	v_fmac_f32_dpp v22, v20, v68 row_ror:1 row_mask:0xf bank_mask:0xf bound_ctrl:1
	v_add_f32_e32 v18, 1.0, v18
	v_rcp_f32_e32 v18, v18
	v_fmac_f32_dpp v22, v21, v80 row_ror:15 row_mask:0xf bank_mask:0xf bound_ctrl:1
	v_mul_f32_e32 v20, v22, v24
	v_cndmask_b32_e64 v19, v11, v19, s[42:43]
	v_mul_f32_e32 v18, v20, v18
	v_cndmask_b32_e64 v20, v15, v23, s[42:43]
	v_cndmask_b32_e64 v22, v11, v3, s[40:41]
	v_fma_f32 v23, v11, v85, v97
	v_fmac_f32_dpp v23, v19, v73 row_ror:1 row_mask:0xf bank_mask:0xf bound_ctrl:1
	v_cndmask_b32_e64 v21, v15, v7, s[40:41]
	v_fmac_f32_dpp v23, v22, v89 row_ror:15 row_mask:0xf bank_mask:0xf bound_ctrl:1
	v_mul_f32_e32 v19, 0xbfb8aa3b, v23
	v_exp_f32_e32 v19, v19
	v_fma_f32 v22, v15, v77, v93
	v_fmac_f32_dpp v22, v20, v69 row_ror:1 row_mask:0xf bank_mask:0xf bound_ctrl:1
	v_add_f32_e32 v19, 1.0, v19
	v_rcp_f32_e32 v19, v19
	v_fmac_f32_dpp v22, v21, v81 row_ror:15 row_mask:0xf bank_mask:0xf bound_ctrl:1
	v_mul_f32_e32 v20, v22, v23
	v_mul_f32_e32 v19, v20, v19
	v_cvt_pk_bf16_f32 v16, v16, v17
	v_cvt_pk_bf16_f32 v17, v18, v19
	s_nop 0
	v_mov_b32_e32 v116, v216
	v_mov_b32_e32 v117, v217
	v_mov_b32_e32 v118, v16
	v_mov_b32_e32 v119, v17
	s_and_saveexec_b64 s[2:3], s[56:57]
	s_cbranch_execz .LBB0_464
	v_mov_b64_e32 v[18:19], s[20:21]
	s_movk_i32 s6, 0x1800
	v_mad_i64_i32 v[18:19], s[6:7], v109, s6, v[18:19]
	v_lshl_add_u64 v[18:19], v[188:189], 1, v[18:19]
	global_store_dwordx4 v[18:19], v[116:119], off
.LBB0_464:
	s_or_b64 exec, exec, s[2:3]
	ds_read_b128 v[16:19], v237 offset:2064
	ds_read_b128 v[20:23], v237 offset:2576
	v_cndmask_b32_e64 v8, v0, v8, s[42:43]
	v_cndmask_b32_e64 v12, v4, v12, s[42:43]
	v_fmac_f32_e32 v97, v3, v85
	s_waitcnt lgkmcnt(0)
	v_cndmask_b32_e64 v20, v0, v20, s[40:41]
	v_fma_f32 v0, v0, v82, v94
	v_fmac_f32_dpp v0, v8, v70 row_ror:1 row_mask:0xf bank_mask:0xf bound_ctrl:1
	v_fmac_f32_dpp v0, v20, v86 row_ror:15 row_mask:0xf bank_mask:0xf bound_ctrl:1
	v_mul_f32_e32 v8, 0xbfb8aa3b, v0
	v_exp_f32_e32 v8, v8
	v_cndmask_b32_e64 v16, v4, v16, s[40:41]
	v_fma_f32 v4, v4, v74, v90
	v_add_f32_e32 v8, 1.0, v8
	v_rcp_f32_e32 v8, v8
	v_fmac_f32_dpp v4, v12, v66 row_ror:1 row_mask:0xf bank_mask:0xf bound_ctrl:1
	v_fmac_f32_dpp v4, v16, v78 row_ror:15 row_mask:0xf bank_mask:0xf bound_ctrl:1
	v_mul_f32_e32 v0, v4, v0
	v_mul_f32_e32 v0, v0, v8
	v_cndmask_b32_e64 v8, v1, v9, s[42:43]
	v_cndmask_b32_e64 v12, v1, v21, s[40:41]
	v_fma_f32 v1, v1, v83, v95
	v_fmac_f32_dpp v1, v8, v71 row_ror:1 row_mask:0xf bank_mask:0xf bound_ctrl:1
	v_cndmask_b32_e64 v4, v5, v13, s[42:43]
	v_fmac_f32_dpp v1, v12, v87 row_ror:15 row_mask:0xf bank_mask:0xf bound_ctrl:1
	v_mul_f32_e32 v8, 0xbfb8aa3b, v1
	v_exp_f32_e32 v8, v8
	v_cndmask_b32_e64 v9, v5, v17, s[40:41]
	v_fma_f32 v5, v5, v75, v91
	v_fmac_f32_dpp v5, v4, v67 row_ror:1 row_mask:0xf bank_mask:0xf bound_ctrl:1
	v_add_f32_e32 v4, 1.0, v8
	v_fmac_f32_dpp v5, v9, v79 row_ror:15 row_mask:0xf bank_mask:0xf bound_ctrl:1
	v_mul_f32_e32 v1, v5, v1
	v_cndmask_b32_e64 v5, v2, v10, s[42:43]
	v_cndmask_b32_e64 v9, v2, v22, s[40:41]
	v_fma_f32 v2, v2, v84, v96
	v_fmac_f32_dpp v2, v5, v72 row_ror:1 row_mask:0xf bank_mask:0xf bound_ctrl:1
	v_rcp_f32_e32 v4, v4
	v_fmac_f32_dpp v2, v9, v88 row_ror:15 row_mask:0xf bank_mask:0xf bound_ctrl:1
	v_mul_f32_e32 v5, 0xbfb8aa3b, v2
	v_exp_f32_e32 v5, v5
	v_mul_f32_e32 v1, v1, v4
	v_cndmask_b32_e64 v4, v6, v14, s[42:43]
	v_cndmask_b32_e64 v8, v6, v18, s[40:41]
	v_fma_f32 v6, v6, v76, v92
	v_fmac_f32_dpp v6, v4, v68 row_ror:1 row_mask:0xf bank_mask:0xf bound_ctrl:1
	v_add_f32_e32 v4, 1.0, v5
	v_fmac_f32_dpp v6, v8, v80 row_ror:15 row_mask:0xf bank_mask:0xf bound_ctrl:1
	v_cndmask_b32_e64 v5, v3, v11, s[42:43]
	v_cndmask_b32_e64 v8, v3, v23, s[40:41]
	v_rcp_f32_e32 v4, v4
	v_fmac_f32_dpp v97, v5, v73 row_ror:1 row_mask:0xf bank_mask:0xf bound_ctrl:1
	v_mul_f32_e32 v2, v6, v2
	v_fmac_f32_dpp v97, v8, v89 row_ror:15 row_mask:0xf bank_mask:0xf bound_ctrl:1
	v_mul_f32_e32 v3, 0xbfb8aa3b, v97
	v_exp_f32_e32 v3, v3
	v_mul_f32_e32 v2, v2, v4
	v_cndmask_b32_e64 v4, v7, v15, s[42:43]
	v_cndmask_b32_e64 v6, v7, v19, s[40:41]
	v_add_f32_e32 v3, 1.0, v3
	v_fmac_f32_e32 v93, v7, v77
	v_rcp_f32_e32 v3, v3
	v_fmac_f32_dpp v93, v4, v69 row_ror:1 row_mask:0xf bank_mask:0xf bound_ctrl:1
	v_fmac_f32_dpp v93, v6, v81 row_ror:15 row_mask:0xf bank_mask:0xf bound_ctrl:1
	v_mul_f32_e32 v4, v93, v97
	v_mul_f32_e32 v3, v4, v3
	v_cvt_pk_bf16_f32 v134, v0, v1
	v_cvt_pk_bf16_f32 v135, v2, v3
	s_nop 0
	v_mov_b32_e32 v116, v218
	v_mov_b32_e32 v117, v219
	v_mov_b32_e32 v118, v134
	v_mov_b32_e32 v119, v135
	s_and_saveexec_b64 s[2:3], s[34:35]
	s_cbranch_execz .LBB0_382
	v_mov_b64_e32 v[0:1], s[20:21]
	s_movk_i32 s6, 0x1800
	v_mad_i64_i32 v[136:137], s[6:7], v107, s6, v[0:1]
	v_lshl_add_u64 v[0:1], v[188:189], 1, v[136:137]
	global_store_dwordx4 v[0:1], v[116:119], off
	s_branch .LBB0_382
